# P5 x^T fragments: one 16-byte load per MFMA operand (32 contiguous bytes per row per instruction) plus two half-wave permlane32 swaps, instead of two 8-byte loads
# speedup vs baseline: 1.0320x; 1.0005x over previous
; #define LAS __attribute__((address_space(3)))
; __device__ __forceinline__ f32x16 mfma32(bf16x8 a, bf16x8 b, f32x16 c) { return __builtin_amdgcn_mfma_f32_32x32x16_bf16(a, b, c, 0, 0, 0); }
; __device__ __forceinline__ void phase_ssd_y(const PT& p, LAS unsigned char* lds, int tid, int lane, int wave) {
;     ...
;             const bf16* pp = PV + ((size_t)(bc * 32 + hh) * 64 + pb * 32 + r32) * 128 + 8 * h;
; #pragma unroll
;             for (int st = 0; st < 8; ++st) acc = mfma32(ld_frag16(pp + 16 * st), cf[st], acc);
;             const float al = acum[r * 128 + l]; const float el = __expf(al); const float dsk = p.in[11][hh];
; #pragma unroll
;             for (int i = 0; i < 16; ++i) acc[i] *= el;
;             const bf16* xrow = xT + ((size_t)bc * 2048 + hh * 64 + pb * 32 + r32) * 128 + 4 * h;
; #pragma unroll
;             for (int sb = 0; sb < 4; ++sb) {
;                 if (sb <= lb) {
;                     f32x16 mm;
; #pragma unroll
;                     for (int qd = 0; qd < 4; ++qd) {
;                         const int s0 = sb * 32 + 8 * qd + 4 * h;
;                         const f32x4 as = *(const LAS f32x4*)(acum + r * 128 + s0), ds = *(const LAS f32x4*)(dtt + r * 128 + s0);
; #pragma unroll
;                         for (int j = 0; j < 4; ++j) { const float v = X[sb][4 * qd + j] * __expf(al - as[j]) * ds[j]; mm[4 * qd + j] = (s0 + j < l) ? v : ((s0 + j == l) ? v + dsk : 0.f); }
;                     }
; #pragma unroll
;                     for (int s2 = 0; s2 < 2; ++s2) acc = mfma32(ld_frag8x2(xrow + sb * 32 + 16 * s2), pack_frag(mm, s2), acc);
.Lp5v3:
	v_lshl_add_u64 v[212:213], v[142:143], 0, s[94:95]
	v_lshl_add_u64 v[206:207], v[144:145], 0, s[94:95]
	v_mov_b32_e32 v164, 0
	v_add_co_u32_e32 v206, vcc, 0x1a900000, v206
	s_nop 1
	v_addc_co_u32_e32 v207, vcc, 0, v207, vcc
	v_bfe_u32 v164, v117, 5, 1
	v_lshlrev_b32_e32 v164, 3, v164
	v_add_co_u32_e32 v206, vcc, v164, v206
	s_nop 1
	v_addc_co_u32_e32 v207, vcc, 0, v207, vcc
	v_mov_b32_e32 v164, 0
	v_add_co_u32_e32 v184, vcc, 0x4000, v206
	s_nop 1
	v_addc_co_u32_e32 v185, vcc, 0, v207, vcc
	global_load_dword v159, v164, s[84:85]
	global_load_dwordx4 v[170:173], v[212:213], off
	global_load_dwordx4 v[174:177], v[212:213], off offset:32
	global_load_dwordx4 v[178:181], v[212:213], off offset:64
	global_load_dwordx4 v[220:223], v[212:213], off offset:96
	global_load_dwordx4 v[224:227], v[212:213], off offset:128
	global_load_dwordx4 v[228:231], v[212:213], off offset:160
	global_load_dwordx4 v[232:235], v[212:213], off offset:192
	global_load_dwordx4 v[208:211], v[212:213], off offset:224
	global_load_dwordx4 v[150:153], v[206:207], off offset:0
	global_load_dwordx4 v[154:157], v[206:207], off offset:32
	global_load_dwordx4 v[192:195], v[206:207], off offset:64
	global_load_dwordx4 v[198:201], v[206:207], off offset:96
	global_load_dwordx4 v[112:115], v[206:207], off offset:128
	global_load_dwordx4 v[202:205], v[206:207], off offset:160
	global_load_dwordx4 v[240:243], v[206:207], off offset:192
	global_load_dwordx4 v[146:149], v[206:207], off offset:224
	s_waitcnt vmcnt(0)
.Lp5v3_head:
	s_add_u32 s100, s94, 0x4000
	s_mov_b32 s101, 0
	ds_read_b32 v158, v141
	v_lshl_add_u64 v[212:213], v[142:143], 0, s[100:101]
	s_waitcnt vmcnt(16)
	v_mfma_f32_32x32x16_bf16 v[64:79], v[170:173], v[80:83], 0
	global_load_dwordx4 v[170:173], v[212:213], off
	s_waitcnt vmcnt(16)
	v_mfma_f32_32x32x16_bf16 v[64:79], v[174:177], v[84:87], v[64:79]
	global_load_dwordx4 v[174:177], v[212:213], off offset:32
	s_waitcnt vmcnt(16)
	v_mfma_f32_32x32x16_bf16 v[64:79], v[178:181], v[88:91], v[64:79]
	global_load_dwordx4 v[178:181], v[212:213], off offset:64
	s_waitcnt vmcnt(16)
	v_mfma_f32_32x32x16_bf16 v[64:79], v[220:223], v[92:95], v[64:79]
	global_load_dwordx4 v[220:223], v[212:213], off offset:96
	s_waitcnt vmcnt(16)
	v_mfma_f32_32x32x16_bf16 v[64:79], v[224:227], v[96:99], v[64:79]
	global_load_dwordx4 v[224:227], v[212:213], off offset:128
	s_waitcnt vmcnt(16)
	v_mfma_f32_32x32x16_bf16 v[64:79], v[228:231], v[100:103], v[64:79]
	global_load_dwordx4 v[228:231], v[212:213], off offset:160
	s_waitcnt vmcnt(16)
	v_mfma_f32_32x32x16_bf16 v[64:79], v[232:235], v[104:107], v[64:79]
	global_load_dwordx4 v[232:235], v[212:213], off offset:192
	s_waitcnt vmcnt(16)
	v_mfma_f32_32x32x16_bf16 v[64:79], v[208:211], v[108:111], v[64:79]
	global_load_dwordx4 v[208:211], v[212:213], off offset:224
	s_waitcnt lgkmcnt(0)
	v_mul_f32_e32 v164, 0x3fb8aa3b, v158
	v_exp_f32_e32 v165, v164
	v_mov_b32_e32 v158, v164
	s_nop 8
	v_mul_f32_e32 v64, v165, v64
	v_mul_f32_e32 v65, v165, v65
	v_mul_f32_e32 v66, v165, v66
	v_mul_f32_e32 v67, v165, v67
	v_mul_f32_e32 v68, v165, v68
	v_mul_f32_e32 v69, v165, v69
	v_mul_f32_e32 v70, v165, v70
	v_mul_f32_e32 v71, v165, v71
	v_mul_f32_e32 v72, v165, v72
	v_mul_f32_e32 v73, v165, v73
	v_mul_f32_e32 v74, v165, v74
	v_mul_f32_e32 v75, v165, v75
	v_mul_f32_e32 v76, v165, v76
	v_mul_f32_e32 v77, v165, v77
	v_mul_f32_e32 v78, v165, v78
	v_mul_f32_e32 v79, v165, v79
	ds_read_b128 v[236:239], v161 offset:4096
	ds_read_b128 v[250:253], v161 offset:4128
	s_waitcnt lgkmcnt(1)
	v_add_f32_e32 v164, v158, v236
	v_add_f32_e32 v165, v158, v237
	v_add_f32_e32 v244, v158, v238
	v_add_f32_e32 v245, v158, v239
	v_exp_f32_e32 v164, v164
	v_exp_f32_e32 v165, v165
	v_exp_f32_e32 v244, v244
	v_exp_f32_e32 v245, v245
	ds_read_b128 v[236:239], v161 offset:4160
	v_mul_f32_e32 v212, v0, v164
	v_mul_f32_e32 v213, v1, v165
	v_mul_f32_e32 v214, v2, v244
	v_mul_f32_e32 v215, v3, v245
	s_waitcnt lgkmcnt(1)
	v_add_f32_e32 v164, v158, v250
	v_add_f32_e32 v165, v158, v251
	v_add_f32_e32 v244, v158, v252
	v_add_f32_e32 v245, v158, v253
	v_exp_f32_e32 v164, v164
	v_exp_f32_e32 v165, v165
	v_exp_f32_e32 v244, v244
	v_exp_f32_e32 v245, v245
	ds_read_b128 v[250:253], v161 offset:4192
	v_mul_f32_e32 v216, v4, v164
	v_mul_f32_e32 v217, v5, v165
	v_mul_f32_e32 v218, v6, v244
	v_mul_f32_e32 v219, v7, v245
	v_cvt_pk_bf16_f32 v212, v212, v213
	v_cvt_pk_bf16_f32 v213, v214, v215
	v_cvt_pk_bf16_f32 v214, v216, v217
	v_cvt_pk_bf16_f32 v215, v218, v219
	s_nop 0
	s_waitcnt vmcnt(15)
	v_permlane32_swap_b32_e32 v150, v152
	v_permlane32_swap_b32_e32 v151, v153
	v_permlane32_swap_b32_e32 v154, v156
	v_permlane32_swap_b32_e32 v155, v157
	s_nop 1
	v_mfma_f32_32x32x16_bf16 v[64:79], v[150:153], v[212:215], v[64:79]
	s_waitcnt lgkmcnt(1)
	v_add_f32_e32 v164, v158, v236
	v_add_f32_e32 v165, v158, v237
	v_add_f32_e32 v244, v158, v238
	v_add_f32_e32 v245, v158, v239
	v_exp_f32_e32 v164, v164
	v_exp_f32_e32 v165, v165
	v_exp_f32_e32 v244, v244
	v_exp_f32_e32 v245, v245
	v_mul_f32_e32 v212, v8, v164
	v_mul_f32_e32 v213, v9, v165
	v_mul_f32_e32 v214, v10, v244
	v_mul_f32_e32 v215, v11, v245
	s_waitcnt lgkmcnt(0)
	v_add_f32_e32 v164, v158, v250
	v_add_f32_e32 v165, v158, v251
	v_add_f32_e32 v244, v158, v252
	v_add_f32_e32 v245, v158, v253
	v_exp_f32_e32 v164, v164
	v_exp_f32_e32 v165, v165
	v_exp_f32_e32 v244, v244
	v_exp_f32_e32 v245, v245
	v_mul_f32_e32 v216, v12, v164
	v_mul_f32_e32 v217, v13, v165
	v_mul_f32_e32 v218, v14, v244
	v_mul_f32_e32 v219, v15, v245
	v_cvt_pk_bf16_f32 v212, v212, v213
	v_cvt_pk_bf16_f32 v213, v214, v215
	v_cvt_pk_bf16_f32 v214, v216, v217
	v_cvt_pk_bf16_f32 v215, v218, v219
	s_nop 0
	s_nop 0
	v_mfma_f32_32x32x16_bf16 v[64:79], v[154:157], v[212:215], v[64:79]
	global_load_dwordx4 v[150:153], v[184:185], off offset:0
	global_load_dwordx4 v[154:157], v[184:185], off offset:32
	ds_read_b128 v[236:239], v161 offset:4224
	ds_read_b128 v[250:253], v161 offset:4256
	s_waitcnt lgkmcnt(1)
; #define LAS __attribute__((address_space(3)))
; __device__ __forceinline__ f32x16 mfma32(bf16x8 a, bf16x8 b, f32x16 c) { return __builtin_amdgcn_mfma_f32_32x32x16_bf16(a, b, c, 0, 0, 0); }
; __device__ __forceinline__ void phase_ssd_y(const PT& p, LAS unsigned char* lds, int tid, int lane, int wave) {
;     ...
;             for (int sb = 0; sb < 4; ++sb) {
;                 if (sb <= lb) {
;                     f32x16 mm;
; #pragma unroll
;                     for (int qd = 0; qd < 4; ++qd) {
;                         const int s0 = sb * 32 + 8 * qd + 4 * h;
;                         const f32x4 as = *(const LAS f32x4*)(acum + r * 128 + s0), ds = *(const LAS f32x4*)(dtt + r * 128 + s0);
; #pragma unroll
;                         for (int j = 0; j < 4; ++j) { const float v = X[sb][4 * qd + j] * __expf(al - as[j]) * ds[j]; mm[4 * qd + j] = (s0 + j < l) ? v : ((s0 + j == l) ? v + dsk : 0.f); }
;                     }
; #pragma unroll
;                     for (int s2 = 0; s2 < 2; ++s2) acc = mfma32(ld_frag8x2(xrow + sb * 32 + 16 * s2), pack_frag(mm, s2), acc);
	v_add_f32_e32 v164, v158, v236
	v_add_f32_e32 v165, v158, v237
	v_add_f32_e32 v244, v158, v238
	v_add_f32_e32 v245, v158, v239
	v_exp_f32_e32 v164, v164
	v_exp_f32_e32 v165, v165
	v_exp_f32_e32 v244, v244
	v_exp_f32_e32 v245, v245
	ds_read_b128 v[236:239], v161 offset:4288
	v_mul_f32_e32 v212, v16, v164
	v_mul_f32_e32 v213, v17, v165
	v_mul_f32_e32 v214, v18, v244
	v_mul_f32_e32 v215, v19, v245
	s_waitcnt lgkmcnt(1)
	v_add_f32_e32 v164, v158, v250
	v_add_f32_e32 v165, v158, v251
	v_add_f32_e32 v244, v158, v252
	v_add_f32_e32 v245, v158, v253
	v_exp_f32_e32 v164, v164
	v_exp_f32_e32 v165, v165
	v_exp_f32_e32 v244, v244
	v_exp_f32_e32 v245, v245
	ds_read_b128 v[250:253], v161 offset:4320
	v_mul_f32_e32 v216, v20, v164
	v_mul_f32_e32 v217, v21, v165
	v_mul_f32_e32 v218, v22, v244
	v_mul_f32_e32 v219, v23, v245
	v_cvt_pk_bf16_f32 v212, v212, v213
	v_cvt_pk_bf16_f32 v213, v214, v215
	v_cvt_pk_bf16_f32 v214, v216, v217
	v_cvt_pk_bf16_f32 v215, v218, v219
	s_nop 0
	s_waitcnt vmcnt(15)
	v_permlane32_swap_b32_e32 v192, v194
	v_permlane32_swap_b32_e32 v193, v195
	v_permlane32_swap_b32_e32 v198, v200
	v_permlane32_swap_b32_e32 v199, v201
	s_nop 1
	v_mfma_f32_32x32x16_bf16 v[64:79], v[192:195], v[212:215], v[64:79]
	s_waitcnt lgkmcnt(1)
	v_add_f32_e32 v164, v158, v236
	v_add_f32_e32 v165, v158, v237
	v_add_f32_e32 v244, v158, v238
	v_add_f32_e32 v245, v158, v239
	v_exp_f32_e32 v164, v164
	v_exp_f32_e32 v165, v165
	v_exp_f32_e32 v244, v244
	v_exp_f32_e32 v245, v245
	v_mul_f32_e32 v212, v24, v164
	v_mul_f32_e32 v213, v25, v165
	v_mul_f32_e32 v214, v26, v244
	v_mul_f32_e32 v215, v27, v245
	s_waitcnt lgkmcnt(0)
	v_add_f32_e32 v164, v158, v250
	v_add_f32_e32 v165, v158, v251
	v_add_f32_e32 v244, v158, v252
	v_add_f32_e32 v245, v158, v253
	v_exp_f32_e32 v164, v164
	v_exp_f32_e32 v165, v165
	v_exp_f32_e32 v244, v244
	v_exp_f32_e32 v245, v245
	v_mul_f32_e32 v216, v28, v164
	v_mul_f32_e32 v217, v29, v165
	v_mul_f32_e32 v218, v30, v244
	v_mul_f32_e32 v219, v31, v245
	v_cvt_pk_bf16_f32 v212, v212, v213
	v_cvt_pk_bf16_f32 v213, v214, v215
	v_cvt_pk_bf16_f32 v214, v216, v217
	v_cvt_pk_bf16_f32 v215, v218, v219
	s_nop 0
	s_nop 0
	v_mfma_f32_32x32x16_bf16 v[64:79], v[198:201], v[212:215], v[64:79]
	global_load_dwordx4 v[192:195], v[184:185], off offset:64
	global_load_dwordx4 v[198:201], v[184:185], off offset:96
	ds_read_b128 v[236:239], v161 offset:4352
	ds_read_b128 v[250:253], v161 offset:4384
	s_waitcnt lgkmcnt(1)
	v_add_f32_e32 v164, v158, v236
	v_add_f32_e32 v165, v158, v237
	v_add_f32_e32 v244, v158, v238
	v_add_f32_e32 v245, v158, v239
	v_exp_f32_e32 v164, v164
	v_exp_f32_e32 v165, v165
	v_exp_f32_e32 v244, v244
	v_exp_f32_e32 v245, v245
	ds_read_b128 v[236:239], v161 offset:4416
	v_mul_f32_e32 v212, v48, v164
	v_mul_f32_e32 v213, v49, v165
	v_mul_f32_e32 v214, v50, v244
	v_mul_f32_e32 v215, v51, v245
	s_waitcnt lgkmcnt(1)
	v_add_f32_e32 v164, v158, v250
	v_add_f32_e32 v165, v158, v251
	v_add_f32_e32 v244, v158, v252
	v_add_f32_e32 v245, v158, v253
	v_exp_f32_e32 v164, v164
	v_exp_f32_e32 v165, v165
	v_exp_f32_e32 v244, v244
	v_exp_f32_e32 v245, v245
	ds_read_b128 v[250:253], v161 offset:4448
	v_mul_f32_e32 v216, v52, v164
	v_mul_f32_e32 v217, v53, v165
	v_mul_f32_e32 v218, v54, v244
	v_mul_f32_e32 v219, v55, v245
	v_cvt_pk_bf16_f32 v212, v212, v213
	v_cvt_pk_bf16_f32 v213, v214, v215
	v_cvt_pk_bf16_f32 v214, v216, v217
	v_cvt_pk_bf16_f32 v215, v218, v219
	s_nop 0
	s_waitcnt vmcnt(15)
	v_permlane32_swap_b32_e32 v112, v114
	v_permlane32_swap_b32_e32 v113, v115
	v_permlane32_swap_b32_e32 v202, v204
	v_permlane32_swap_b32_e32 v203, v205
	s_nop 1
	v_mfma_f32_32x32x16_bf16 v[64:79], v[112:115], v[212:215], v[64:79]
	s_waitcnt lgkmcnt(1)
	v_add_f32_e32 v164, v158, v236
	v_add_f32_e32 v165, v158, v237
	v_add_f32_e32 v244, v158, v238
	v_add_f32_e32 v245, v158, v239
	v_exp_f32_e32 v164, v164
	v_exp_f32_e32 v165, v165
	v_exp_f32_e32 v244, v244
	v_exp_f32_e32 v245, v245
	v_mul_f32_e32 v212, v56, v164
	v_mul_f32_e32 v213, v57, v165
	v_mul_f32_e32 v214, v58, v244
	v_mul_f32_e32 v215, v59, v245
	s_waitcnt lgkmcnt(0)
	v_add_f32_e32 v164, v158, v250
	v_add_f32_e32 v165, v158, v251
	v_add_f32_e32 v244, v158, v252
	v_add_f32_e32 v245, v158, v253
	v_exp_f32_e32 v164, v164
	v_exp_f32_e32 v165, v165
	v_exp_f32_e32 v244, v244
	v_exp_f32_e32 v245, v245
	v_mul_f32_e32 v216, v60, v164
	v_mul_f32_e32 v217, v61, v165
	v_mul_f32_e32 v218, v62, v244
	v_mul_f32_e32 v219, v63, v245
	v_cvt_pk_bf16_f32 v212, v212, v213
	v_cvt_pk_bf16_f32 v213, v214, v215
	v_cvt_pk_bf16_f32 v214, v216, v217
	v_cvt_pk_bf16_f32 v215, v218, v219
	s_nop 0
	s_nop 0
	v_mfma_f32_32x32x16_bf16 v[64:79], v[202:205], v[212:215], v[64:79]
	global_load_dwordx4 v[112:115], v[184:185], off offset:128
	global_load_dwordx4 v[202:205], v[184:185], off offset:160
	ds_read_b128 v[236:239], v161 offset:4480
	ds_read_b128 v[250:253], v161 offset:4512
	s_waitcnt lgkmcnt(1)
	v_add_f32_e32 v164, v158, v236
	v_add_f32_e32 v165, v158, v237
	v_add_f32_e32 v244, v158, v238
	v_add_f32_e32 v245, v158, v239
	v_exp_f32_e32 v164, v164
	v_exp_f32_e32 v165, v165
	v_exp_f32_e32 v244, v244
	v_exp_f32_e32 v245, v245
	ds_read_b128 v[236:239], v161 offset:4544
	v_mul_f32_e32 v212, v32, v164
	v_mul_f32_e32 v213, v33, v165
	v_mul_f32_e32 v214, v34, v244
	v_mul_f32_e32 v215, v35, v245
	s_waitcnt lgkmcnt(1)
	v_add_f32_e32 v164, v158, v250
	v_add_f32_e32 v165, v158, v251
	v_add_f32_e32 v244, v158, v252
	v_add_f32_e32 v245, v158, v253
	v_exp_f32_e32 v164, v164
	v_exp_f32_e32 v165, v165
	v_exp_f32_e32 v244, v244
	v_exp_f32_e32 v245, v245
	ds_read_b128 v[250:253], v161 offset:4576
	v_mul_f32_e32 v216, v36, v164
	v_mul_f32_e32 v217, v37, v165
	v_mul_f32_e32 v218, v38, v244
	v_mul_f32_e32 v219, v39, v245
	s_waitcnt vmcnt(16)
; #define LAS __attribute__((address_space(3)))
; __device__ __forceinline__ float bflo(unsigned u) { return __uint_as_float(u << 16); }
; __device__ __forceinline__ float bfhi(unsigned u) { return __uint_as_float(u & 0xffff0000u); }
; __device__ __forceinline__ f32x16 mfma32(bf16x8 a, bf16x8 b, f32x16 c) { return __builtin_amdgcn_mfma_f32_32x32x16_bf16(a, b, c, 0, 0, 0); }
; __device__ __forceinline__ void phase_ssd_y(const PT& p, LAS unsigned char* lds, int tid, int lane, int wave) {
;     ...
;             for (int sb = 0; sb < 4; ++sb) {
;                 if (sb <= lb) {
;                     f32x16 mm;
; #pragma unroll
;                     for (int qd = 0; qd < 4; ++qd) {
;                         const int s0 = sb * 32 + 8 * qd + 4 * h;
;                         const f32x4 as = *(const LAS f32x4*)(acum + r * 128 + s0), ds = *(const LAS f32x4*)(dtt + r * 128 + s0);
; #pragma unroll
;                         for (int j = 0; j < 4; ++j) { const float v = X[sb][4 * qd + j] * __expf(al - as[j]) * ds[j]; mm[4 * qd + j] = (s0 + j < l) ? v : ((s0 + j == l) ? v + dsk : 0.f); }
;                     }
; #pragma unroll
;                     for (int s2 = 0; s2 < 2; ++s2) acc = mfma32(ld_frag8x2(xrow + sb * 32 + 16 * s2), pack_frag(mm, s2), acc);
;                 }
;             }
; #pragma unroll
;             for (int qd = 0; qd < 4; ++qd) {
;                 LAS u32x2* yp = (LAS u32x2*)(tile + l * SY_TP + (r * 64 + pb * 32 + 8 * qd + 4 * h) * 2); const u32x2 zz = *yp;
;                 const float y0 = acc[4 * qd] * bflo(zz.x), y1 = acc[4 * qd + 1] * bfhi(zz.x);
;                 const float y2 = acc[4 * qd + 2] * bflo(zz.y), y3 = acc[4 * qd + 3] * bfhi(zz.y);
;                 ssq += (y0 * y0 + y1 * y1) + (y2 * y2 + y3 * y3);
;                 u32x2 w; w.x = pk2(y0, y1); w.y = pk2(y2, y3); *yp = w;
;             }
	v_add_f32_e32 v169, v212, v159
	v_add_f32_e32 v183, v213, v159
	v_cmp_eq_u32_e32 vcc, 0, v160
	v_cmp_eq_u32_e64 s[100:101], 1, v160
	s_nop 0
	v_cndmask_b32_e32 v169, 0, v169, vcc
	v_cndmask_b32_e64 v183, 0, v183, s[100:101]
	v_cmp_lt_i32_e32 vcc, 0, v160
	v_cmp_lt_i32_e64 s[100:101], 1, v160
	s_nop 0
	v_cndmask_b32_e32 v212, v169, v212, vcc
	v_cndmask_b32_e64 v213, v183, v213, s[100:101]
	v_add_f32_e32 v169, v214, v159
	v_add_f32_e32 v183, v215, v159
	v_cmp_eq_u32_e32 vcc, 2, v160
	v_cmp_eq_u32_e64 s[100:101], 3, v160
	s_nop 0
	v_cndmask_b32_e32 v169, 0, v169, vcc
	v_cndmask_b32_e64 v183, 0, v183, s[100:101]
	v_cmp_lt_i32_e32 vcc, 2, v160
	v_cmp_lt_i32_e64 s[100:101], 3, v160
	s_nop 0
	v_cndmask_b32_e32 v214, v169, v214, vcc
	v_cndmask_b32_e64 v215, v183, v215, s[100:101]
	v_add_f32_e32 v169, v216, v159
	v_add_f32_e32 v183, v217, v159
	v_cmp_eq_u32_e32 vcc, 8, v160
	v_cmp_eq_u32_e64 s[100:101], 9, v160
	s_nop 0
	v_cndmask_b32_e32 v169, 0, v169, vcc
	v_cndmask_b32_e64 v183, 0, v183, s[100:101]
	v_cmp_lt_i32_e32 vcc, 8, v160
	v_cmp_lt_i32_e64 s[100:101], 9, v160
	s_nop 0
	v_cndmask_b32_e32 v216, v169, v216, vcc
	v_cndmask_b32_e64 v217, v183, v217, s[100:101]
	v_add_f32_e32 v169, v218, v159
	v_add_f32_e32 v183, v219, v159
	v_cmp_eq_u32_e32 vcc, 10, v160
	v_cmp_eq_u32_e64 s[100:101], 11, v160
	s_nop 0
	v_cndmask_b32_e32 v169, 0, v169, vcc
	v_cndmask_b32_e64 v183, 0, v183, s[100:101]
	v_cmp_lt_i32_e32 vcc, 10, v160
	v_cmp_lt_i32_e64 s[100:101], 11, v160
	s_nop 0
	v_cndmask_b32_e32 v218, v169, v218, vcc
	v_cndmask_b32_e64 v219, v183, v219, s[100:101]
	v_cvt_pk_bf16_f32 v212, v212, v213
	v_cvt_pk_bf16_f32 v213, v214, v215
	v_cvt_pk_bf16_f32 v214, v216, v217
	v_cvt_pk_bf16_f32 v215, v218, v219
	s_nop 0
	s_waitcnt vmcnt(14)
	v_permlane32_swap_b32_e32 v240, v242
	v_permlane32_swap_b32_e32 v241, v243
	v_permlane32_swap_b32_e32 v146, v148
	v_permlane32_swap_b32_e32 v147, v149
	s_nop 1
	v_mfma_f32_32x32x16_bf16 v[64:79], v[240:243], v[212:215], v[64:79]
	s_waitcnt lgkmcnt(1)
	v_add_f32_e32 v164, v158, v236
	v_add_f32_e32 v165, v158, v237
	v_add_f32_e32 v244, v158, v238
	v_add_f32_e32 v245, v158, v239
	v_exp_f32_e32 v164, v164
	v_exp_f32_e32 v165, v165
	v_exp_f32_e32 v244, v244
	v_exp_f32_e32 v245, v245
	v_mul_f32_e32 v212, v40, v164
	v_mul_f32_e32 v213, v41, v165
	v_mul_f32_e32 v214, v42, v244
	v_mul_f32_e32 v215, v43, v245
	s_waitcnt lgkmcnt(0)
	v_add_f32_e32 v164, v158, v250
	v_add_f32_e32 v165, v158, v251
	v_add_f32_e32 v244, v158, v252
	v_add_f32_e32 v245, v158, v253
	v_exp_f32_e32 v164, v164
	v_exp_f32_e32 v165, v165
	v_exp_f32_e32 v244, v244
	v_exp_f32_e32 v245, v245
	v_mul_f32_e32 v216, v44, v164
	v_mul_f32_e32 v217, v45, v165
	v_mul_f32_e32 v218, v46, v244
	v_mul_f32_e32 v219, v47, v245
	v_add_f32_e32 v169, v212, v159
	v_add_f32_e32 v183, v213, v159
	v_cmp_eq_u32_e32 vcc, 16, v160
	v_cmp_eq_u32_e64 s[100:101], 17, v160
	s_nop 0
	v_cndmask_b32_e32 v169, 0, v169, vcc
	v_cndmask_b32_e64 v183, 0, v183, s[100:101]
	v_cmp_lt_i32_e32 vcc, 16, v160
	v_cmp_lt_i32_e64 s[100:101], 17, v160
	s_nop 0
	v_cndmask_b32_e32 v212, v169, v212, vcc
	v_cndmask_b32_e64 v213, v183, v213, s[100:101]
	v_add_f32_e32 v169, v214, v159
	v_add_f32_e32 v183, v215, v159
	v_cmp_eq_u32_e32 vcc, 18, v160
	v_cmp_eq_u32_e64 s[100:101], 19, v160
	s_nop 0
	v_cndmask_b32_e32 v169, 0, v169, vcc
	v_cndmask_b32_e64 v183, 0, v183, s[100:101]
	v_cmp_lt_i32_e32 vcc, 18, v160
	v_cmp_lt_i32_e64 s[100:101], 19, v160
	s_nop 0
	v_cndmask_b32_e32 v214, v169, v214, vcc
	v_cndmask_b32_e64 v215, v183, v215, s[100:101]
	v_add_f32_e32 v169, v216, v159
	v_add_f32_e32 v183, v217, v159
	v_cmp_eq_u32_e32 vcc, 24, v160
	v_cmp_eq_u32_e64 s[100:101], 25, v160
	s_nop 0
	v_cndmask_b32_e32 v169, 0, v169, vcc
	v_cndmask_b32_e64 v183, 0, v183, s[100:101]
	v_cmp_lt_i32_e32 vcc, 24, v160
	v_cmp_lt_i32_e64 s[100:101], 25, v160
	s_nop 0
	v_cndmask_b32_e32 v216, v169, v216, vcc
	v_cndmask_b32_e64 v217, v183, v217, s[100:101]
	v_add_f32_e32 v169, v218, v159
	v_add_f32_e32 v183, v219, v159
	v_cmp_eq_u32_e32 vcc, 26, v160
	v_cmp_eq_u32_e64 s[100:101], 27, v160
	s_nop 0
	v_cndmask_b32_e32 v169, 0, v169, vcc
	v_cndmask_b32_e64 v183, 0, v183, s[100:101]
	v_cmp_lt_i32_e32 vcc, 26, v160
	v_cmp_lt_i32_e64 s[100:101], 27, v160
	s_nop 0
	v_cndmask_b32_e32 v218, v169, v218, vcc
	v_cndmask_b32_e64 v219, v183, v219, s[100:101]
	s_cmp_eq_u32 s94, 0x1c000
	s_cselect_b32 s100, 0, 4
	s_add_u32 s84, s84, s100
	s_addc_u32 s85, s85, 0
	v_mov_b32_e32 v164, 0
	global_load_dword v159, v164, s[84:85]
	v_cvt_pk_bf16_f32 v212, v212, v213
	v_cvt_pk_bf16_f32 v213, v214, v215
	v_cvt_pk_bf16_f32 v214, v216, v217
	v_cvt_pk_bf16_f32 v215, v218, v219
	s_nop 0
	s_nop 0
	v_mfma_f32_32x32x16_bf16 v[64:79], v[146:149], v[212:215], v[64:79]
	global_load_dwordx4 v[240:243], v[184:185], off offset:192
	global_load_dwordx4 v[146:149], v[184:185], off offset:224
	s_nop 10
	ds_read_b64 v[216:217], v162 offset:0
	s_waitcnt lgkmcnt(0)
	v_lshlrev_b32_e32 v169, 16, v216
	v_and_b32_e32 v183, 0xffff0000, v216
	v_lshlrev_b32_e32 v254, 16, v217
	v_and_b32_e32 v255, 0xffff0000, v217
	v_mul_f32_e32 v169, v64, v169
	v_mul_f32_e32 v183, v65, v183
	v_mul_f32_e32 v254, v66, v254
	v_mul_f32_e32 v255, v67, v255
	v_mul_f32_e32 v164, v169, v169
	v_mul_f32_e32 v165, v254, v254
	v_fmac_f32_e32 v164, v183, v183
	v_fmac_f32_e32 v165, v255, v255
	v_cvt_pk_bf16_f32 v216, v169, v183
	v_cvt_pk_bf16_f32 v217, v254, v255
	v_add_f32_e32 v164, v164, v165
	ds_write_b64 v162, v[216:217] offset:0
	v_add_f32_e32 v126, v126, v164
	ds_read_b64 v[216:217], v162 offset:16
	s_waitcnt lgkmcnt(0)
; #define LAS __attribute__((address_space(3)))
; __device__ __forceinline__ float bflo(unsigned u) { return __uint_as_float(u << 16); }
; __device__ __forceinline__ float bfhi(unsigned u) { return __uint_as_float(u & 0xffff0000u); }
; __device__ __forceinline__ f32x16 mfma32(bf16x8 a, bf16x8 b, f32x16 c) { return __builtin_amdgcn_mfma_f32_32x32x16_bf16(a, b, c, 0, 0, 0); }
; __device__ __forceinline__ void phase_ssd_y(const PT& p, LAS unsigned char* lds, int tid, int lane, int wave) {
;     ...
;             const bf16* pp = PV + ((size_t)(bc * 32 + hh) * 64 + pb * 32 + r32) * 128 + 8 * h;
; #pragma unroll
;             for (int st = 0; st < 8; ++st) acc = mfma32(ld_frag16(pp + 16 * st), cf[st], acc);
;             const float al = acum[r * 128 + l]; const float el = __expf(al); const float dsk = p.in[11][hh];
; #pragma unroll
;             for (int i = 0; i < 16; ++i) acc[i] *= el;
;     ...
;             for (int qd = 0; qd < 4; ++qd) {
;                 LAS u32x2* yp = (LAS u32x2*)(tile + l * SY_TP + (r * 64 + pb * 32 + 8 * qd + 4 * h) * 2); const u32x2 zz = *yp;
;                 const float y0 = acc[4 * qd] * bflo(zz.x), y1 = acc[4 * qd + 1] * bfhi(zz.x);
;                 const float y2 = acc[4 * qd + 2] * bflo(zz.y), y3 = acc[4 * qd + 3] * bfhi(zz.y);
;                 ssq += (y0 * y0 + y1 * y1) + (y2 * y2 + y3 * y3);
;                 u32x2 w; w.x = pk2(y0, y1); w.y = pk2(y2, y3); *yp = w;
;             }
	v_lshlrev_b32_e32 v169, 16, v216
	v_and_b32_e32 v183, 0xffff0000, v216
	v_lshlrev_b32_e32 v254, 16, v217
	v_and_b32_e32 v255, 0xffff0000, v217
	v_mul_f32_e32 v169, v68, v169
	v_mul_f32_e32 v183, v69, v183
	v_mul_f32_e32 v254, v70, v254
	v_mul_f32_e32 v255, v71, v255
	v_mul_f32_e32 v164, v169, v169
	v_mul_f32_e32 v165, v254, v254
	v_fmac_f32_e32 v164, v183, v183
	v_fmac_f32_e32 v165, v255, v255
	v_cvt_pk_bf16_f32 v216, v169, v183
	v_cvt_pk_bf16_f32 v217, v254, v255
	v_add_f32_e32 v164, v164, v165
	ds_write_b64 v162, v[216:217] offset:16
	v_add_f32_e32 v126, v126, v164
	ds_read_b64 v[216:217], v162 offset:32
	s_waitcnt lgkmcnt(0)
	v_lshlrev_b32_e32 v169, 16, v216
	v_and_b32_e32 v183, 0xffff0000, v216
	v_lshlrev_b32_e32 v254, 16, v217
	v_and_b32_e32 v255, 0xffff0000, v217
	v_mul_f32_e32 v169, v72, v169
	v_mul_f32_e32 v183, v73, v183
	v_mul_f32_e32 v254, v74, v254
	v_mul_f32_e32 v255, v75, v255
	v_mul_f32_e32 v164, v169, v169
	v_mul_f32_e32 v165, v254, v254
	v_fmac_f32_e32 v164, v183, v183
	v_fmac_f32_e32 v165, v255, v255
	v_cvt_pk_bf16_f32 v216, v169, v183
	v_cvt_pk_bf16_f32 v217, v254, v255
	v_add_f32_e32 v164, v164, v165
	ds_write_b64 v162, v[216:217] offset:32
	v_add_f32_e32 v126, v126, v164
	ds_read_b64 v[216:217], v162 offset:48
	s_waitcnt lgkmcnt(0)
	v_lshlrev_b32_e32 v169, 16, v216
	v_and_b32_e32 v183, 0xffff0000, v216
	v_lshlrev_b32_e32 v254, 16, v217
	v_and_b32_e32 v255, 0xffff0000, v217
	v_mul_f32_e32 v169, v76, v169
	v_mul_f32_e32 v183, v77, v183
	v_mul_f32_e32 v254, v78, v254
	v_mul_f32_e32 v255, v79, v255
	v_mul_f32_e32 v164, v169, v169
	v_mul_f32_e32 v165, v254, v254
	v_fmac_f32_e32 v164, v183, v183
	v_fmac_f32_e32 v165, v255, v255
	v_cvt_pk_bf16_f32 v216, v169, v183
	v_cvt_pk_bf16_f32 v217, v254, v255
	v_add_f32_e32 v164, v164, v165
	ds_write_b64 v162, v[216:217] offset:48
	v_add_f32_e32 v126, v126, v164
	v_add_u32_e32 v161, 0x200, v161
	v_add_u32_e32 v141, 0x200, v141
	v_add_u32_e32 v162, 0x80, v162
	v_mov_b32_e32 v206, v184
	v_mov_b32_e32 v207, v185
	v_add_co_u32_e32 v184, vcc, 0x4000, v184
	s_nop 1
	v_addc_co_u32_e32 v185, vcc, 0, v185, vcc
	s_add_u32 s94, s94, 0x4000
	s_cmp_eq_u32 s94, 0x20000
	s_cbranch_scc0 .Lp5v3_head
	s_branch .Lp5v_exit
.Lp5v2:
	v_lshl_add_u64 v[212:213], v[142:143], 0, s[94:95]
	v_lshl_add_u64 v[206:207], v[144:145], 0, s[94:95]
	v_mov_b32_e32 v164, 0
	v_add_co_u32_e32 v206, vcc, 0x1a900000, v206
	s_nop 1
	v_addc_co_u32_e32 v207, vcc, 0, v207, vcc
	v_bfe_u32 v164, v117, 5, 1
	v_lshlrev_b32_e32 v164, 3, v164
	v_add_co_u32_e32 v206, vcc, v164, v206
	s_nop 1
	v_addc_co_u32_e32 v207, vcc, 0, v207, vcc
	v_mov_b32_e32 v164, 0
	v_add_co_u32_e32 v184, vcc, 0x4000, v206
	s_nop 1
	v_addc_co_u32_e32 v185, vcc, 0, v207, vcc
	global_load_dword v159, v164, s[84:85]
	global_load_dwordx4 v[170:173], v[212:213], off
	global_load_dwordx4 v[174:177], v[212:213], off offset:32
	global_load_dwordx4 v[178:181], v[212:213], off offset:64
	global_load_dwordx4 v[220:223], v[212:213], off offset:96
	global_load_dwordx4 v[224:227], v[212:213], off offset:128
	global_load_dwordx4 v[228:231], v[212:213], off offset:160
	global_load_dwordx4 v[232:235], v[212:213], off offset:192
	global_load_dwordx4 v[208:211], v[212:213], off offset:224
	global_load_dwordx4 v[150:153], v[206:207], off offset:0
	global_load_dwordx4 v[154:157], v[206:207], off offset:32
	global_load_dwordx4 v[192:195], v[206:207], off offset:64
	global_load_dwordx4 v[198:201], v[206:207], off offset:96
	global_load_dwordx4 v[112:115], v[206:207], off offset:128
	global_load_dwordx4 v[202:205], v[206:207], off offset:160
	s_waitcnt vmcnt(0)
.Lp5v2_head:
	s_add_u32 s100, s94, 0x4000
	s_mov_b32 s101, 0
	ds_read_b32 v158, v141
	v_lshl_add_u64 v[212:213], v[142:143], 0, s[100:101]
	s_waitcnt vmcnt(14)
	v_mfma_f32_32x32x16_bf16 v[64:79], v[170:173], v[80:83], 0
	global_load_dwordx4 v[170:173], v[212:213], off
	s_waitcnt vmcnt(14)
	v_mfma_f32_32x32x16_bf16 v[64:79], v[174:177], v[84:87], v[64:79]
	global_load_dwordx4 v[174:177], v[212:213], off offset:32
	s_waitcnt vmcnt(14)
	v_mfma_f32_32x32x16_bf16 v[64:79], v[178:181], v[88:91], v[64:79]
	global_load_dwordx4 v[178:181], v[212:213], off offset:64
	s_waitcnt vmcnt(14)
	v_mfma_f32_32x32x16_bf16 v[64:79], v[220:223], v[92:95], v[64:79]
	global_load_dwordx4 v[220:223], v[212:213], off offset:96
	s_waitcnt vmcnt(14)
	v_mfma_f32_32x32x16_bf16 v[64:79], v[224:227], v[96:99], v[64:79]
	global_load_dwordx4 v[224:227], v[212:213], off offset:128
	s_waitcnt vmcnt(14)
	v_mfma_f32_32x32x16_bf16 v[64:79], v[228:231], v[100:103], v[64:79]
	global_load_dwordx4 v[228:231], v[212:213], off offset:160
	s_waitcnt vmcnt(14)
	v_mfma_f32_32x32x16_bf16 v[64:79], v[232:235], v[104:107], v[64:79]
	global_load_dwordx4 v[232:235], v[212:213], off offset:192
	s_waitcnt vmcnt(14)
	v_mfma_f32_32x32x16_bf16 v[64:79], v[208:211], v[108:111], v[64:79]
	global_load_dwordx4 v[208:211], v[212:213], off offset:224
	s_waitcnt lgkmcnt(0)
	v_mul_f32_e32 v164, 0x3fb8aa3b, v158
	v_exp_f32_e32 v165, v164
	v_mov_b32_e32 v158, v164
	s_nop 8
	v_mul_f32_e32 v64, v165, v64
	v_mul_f32_e32 v65, v165, v65
	v_mul_f32_e32 v66, v165, v66
	v_mul_f32_e32 v67, v165, v67
	v_mul_f32_e32 v68, v165, v68
	v_mul_f32_e32 v69, v165, v69
	v_mul_f32_e32 v70, v165, v70
	v_mul_f32_e32 v71, v165, v71
	v_mul_f32_e32 v72, v165, v72
	v_mul_f32_e32 v73, v165, v73
	v_mul_f32_e32 v74, v165, v74
	v_mul_f32_e32 v75, v165, v75
	v_mul_f32_e32 v76, v165, v76
	v_mul_f32_e32 v77, v165, v77
	v_mul_f32_e32 v78, v165, v78
	v_mul_f32_e32 v79, v165, v79
	ds_read_b128 v[236:239], v161 offset:4096
	ds_read_b128 v[250:253], v161 offset:4128
	s_waitcnt lgkmcnt(1)
; #define LAS __attribute__((address_space(3)))
; __device__ __forceinline__ f32x16 mfma32(bf16x8 a, bf16x8 b, f32x16 c) { return __builtin_amdgcn_mfma_f32_32x32x16_bf16(a, b, c, 0, 0, 0); }
; __device__ __forceinline__ void phase_ssd_y(const PT& p, LAS unsigned char* lds, int tid, int lane, int wave) {
;     ...
;             for (int sb = 0; sb < 4; ++sb) {
;                 if (sb <= lb) {
;                     f32x16 mm;
; #pragma unroll
;                     for (int qd = 0; qd < 4; ++qd) {
;                         const int s0 = sb * 32 + 8 * qd + 4 * h;
;                         const f32x4 as = *(const LAS f32x4*)(acum + r * 128 + s0), ds = *(const LAS f32x4*)(dtt + r * 128 + s0);
; #pragma unroll
;                         for (int j = 0; j < 4; ++j) { const float v = X[sb][4 * qd + j] * __expf(al - as[j]) * ds[j]; mm[4 * qd + j] = (s0 + j < l) ? v : ((s0 + j == l) ? v + dsk : 0.f); }
;                     }
; #pragma unroll
;                     for (int s2 = 0; s2 < 2; ++s2) acc = mfma32(ld_frag8x2(xrow + sb * 32 + 16 * s2), pack_frag(mm, s2), acc);
	v_add_f32_e32 v164, v158, v236
	v_add_f32_e32 v165, v158, v237
	v_add_f32_e32 v244, v158, v238
	v_add_f32_e32 v245, v158, v239
	v_exp_f32_e32 v164, v164
	v_exp_f32_e32 v165, v165
	v_exp_f32_e32 v244, v244
	v_exp_f32_e32 v245, v245
	ds_read_b128 v[236:239], v161 offset:4160
	v_mul_f32_e32 v212, v0, v164
	v_mul_f32_e32 v213, v1, v165
	v_mul_f32_e32 v214, v2, v244
	v_mul_f32_e32 v215, v3, v245
	s_waitcnt lgkmcnt(1)
	v_add_f32_e32 v164, v158, v250
	v_add_f32_e32 v165, v158, v251
	v_add_f32_e32 v244, v158, v252
	v_add_f32_e32 v245, v158, v253
	v_exp_f32_e32 v164, v164
	v_exp_f32_e32 v165, v165
	v_exp_f32_e32 v244, v244
	v_exp_f32_e32 v245, v245
	ds_read_b128 v[250:253], v161 offset:4192
	v_mul_f32_e32 v216, v4, v164
	v_mul_f32_e32 v217, v5, v165
	v_mul_f32_e32 v218, v6, v244
	v_mul_f32_e32 v219, v7, v245
	v_cvt_pk_bf16_f32 v212, v212, v213
	v_cvt_pk_bf16_f32 v213, v214, v215
	v_cvt_pk_bf16_f32 v214, v216, v217
	v_cvt_pk_bf16_f32 v215, v218, v219
	s_nop 0
	s_waitcnt vmcnt(13)
	v_permlane32_swap_b32_e32 v150, v152
	v_permlane32_swap_b32_e32 v151, v153
	v_permlane32_swap_b32_e32 v154, v156
	v_permlane32_swap_b32_e32 v155, v157
	s_nop 1
	v_mfma_f32_32x32x16_bf16 v[64:79], v[150:153], v[212:215], v[64:79]
	s_waitcnt lgkmcnt(1)
	v_add_f32_e32 v164, v158, v236
	v_add_f32_e32 v165, v158, v237
	v_add_f32_e32 v244, v158, v238
	v_add_f32_e32 v245, v158, v239
	v_exp_f32_e32 v164, v164
	v_exp_f32_e32 v165, v165
	v_exp_f32_e32 v244, v244
	v_exp_f32_e32 v245, v245
	v_mul_f32_e32 v212, v8, v164
	v_mul_f32_e32 v213, v9, v165
	v_mul_f32_e32 v214, v10, v244
	v_mul_f32_e32 v215, v11, v245
	s_waitcnt lgkmcnt(0)
	v_add_f32_e32 v164, v158, v250
	v_add_f32_e32 v165, v158, v251
	v_add_f32_e32 v244, v158, v252
	v_add_f32_e32 v245, v158, v253
	v_exp_f32_e32 v164, v164
	v_exp_f32_e32 v165, v165
	v_exp_f32_e32 v244, v244
	v_exp_f32_e32 v245, v245
	v_mul_f32_e32 v216, v12, v164
	v_mul_f32_e32 v217, v13, v165
	v_mul_f32_e32 v218, v14, v244
	v_mul_f32_e32 v219, v15, v245
	v_cvt_pk_bf16_f32 v212, v212, v213
	v_cvt_pk_bf16_f32 v213, v214, v215
	v_cvt_pk_bf16_f32 v214, v216, v217
	v_cvt_pk_bf16_f32 v215, v218, v219
	s_nop 0
	s_nop 0
	v_mfma_f32_32x32x16_bf16 v[64:79], v[154:157], v[212:215], v[64:79]
	global_load_dwordx4 v[150:153], v[184:185], off offset:0
	global_load_dwordx4 v[154:157], v[184:185], off offset:32
	ds_read_b128 v[236:239], v161 offset:4224
	ds_read_b128 v[250:253], v161 offset:4256
	s_waitcnt lgkmcnt(1)
	v_add_f32_e32 v164, v158, v236
	v_add_f32_e32 v165, v158, v237
	v_add_f32_e32 v244, v158, v238
	v_add_f32_e32 v245, v158, v239
	v_exp_f32_e32 v164, v164
	v_exp_f32_e32 v165, v165
	v_exp_f32_e32 v244, v244
	v_exp_f32_e32 v245, v245
	ds_read_b128 v[236:239], v161 offset:4288
	v_mul_f32_e32 v212, v16, v164
	v_mul_f32_e32 v213, v17, v165
	v_mul_f32_e32 v214, v18, v244
	v_mul_f32_e32 v215, v19, v245
	s_waitcnt lgkmcnt(1)
	v_add_f32_e32 v164, v158, v250
	v_add_f32_e32 v165, v158, v251
	v_add_f32_e32 v244, v158, v252
	v_add_f32_e32 v245, v158, v253
	v_exp_f32_e32 v164, v164
	v_exp_f32_e32 v165, v165
	v_exp_f32_e32 v244, v244
	v_exp_f32_e32 v245, v245
	ds_read_b128 v[250:253], v161 offset:4320
	v_mul_f32_e32 v216, v20, v164
	v_mul_f32_e32 v217, v21, v165
	v_mul_f32_e32 v218, v22, v244
	v_mul_f32_e32 v219, v23, v245
	v_cvt_pk_bf16_f32 v212, v212, v213
	v_cvt_pk_bf16_f32 v213, v214, v215
	v_cvt_pk_bf16_f32 v214, v216, v217
	v_cvt_pk_bf16_f32 v215, v218, v219
	s_nop 0
	s_waitcnt vmcnt(13)
	v_permlane32_swap_b32_e32 v192, v194
	v_permlane32_swap_b32_e32 v193, v195
	v_permlane32_swap_b32_e32 v198, v200
	v_permlane32_swap_b32_e32 v199, v201
	s_nop 1
	v_mfma_f32_32x32x16_bf16 v[64:79], v[192:195], v[212:215], v[64:79]
	s_waitcnt lgkmcnt(1)
	v_add_f32_e32 v164, v158, v236
	v_add_f32_e32 v165, v158, v237
	v_add_f32_e32 v244, v158, v238
	v_add_f32_e32 v245, v158, v239
	v_exp_f32_e32 v164, v164
	v_exp_f32_e32 v165, v165
	v_exp_f32_e32 v244, v244
	v_exp_f32_e32 v245, v245
	v_mul_f32_e32 v212, v24, v164
	v_mul_f32_e32 v213, v25, v165
	v_mul_f32_e32 v214, v26, v244
	v_mul_f32_e32 v215, v27, v245
	s_waitcnt lgkmcnt(0)
	v_add_f32_e32 v164, v158, v250
	v_add_f32_e32 v165, v158, v251
	v_add_f32_e32 v244, v158, v252
	v_add_f32_e32 v245, v158, v253
	v_exp_f32_e32 v164, v164
	v_exp_f32_e32 v165, v165
	v_exp_f32_e32 v244, v244
	v_exp_f32_e32 v245, v245
	v_mul_f32_e32 v216, v28, v164
	v_mul_f32_e32 v217, v29, v165
	v_mul_f32_e32 v218, v30, v244
	v_mul_f32_e32 v219, v31, v245
	v_cvt_pk_bf16_f32 v212, v212, v213
	v_cvt_pk_bf16_f32 v213, v214, v215
	v_cvt_pk_bf16_f32 v214, v216, v217
	v_cvt_pk_bf16_f32 v215, v218, v219
	s_nop 0
	s_nop 0
	v_mfma_f32_32x32x16_bf16 v[64:79], v[198:201], v[212:215], v[64:79]
	global_load_dwordx4 v[192:195], v[184:185], off offset:64
	global_load_dwordx4 v[198:201], v[184:185], off offset:96
	ds_read_b128 v[236:239], v161 offset:4352
	ds_read_b128 v[250:253], v161 offset:4384
	s_waitcnt lgkmcnt(1)
	v_add_f32_e32 v164, v158, v236
	v_add_f32_e32 v165, v158, v237
	v_add_f32_e32 v244, v158, v238
	v_add_f32_e32 v245, v158, v239
	v_exp_f32_e32 v164, v164
	v_exp_f32_e32 v165, v165
	v_exp_f32_e32 v244, v244
	v_exp_f32_e32 v245, v245
	ds_read_b128 v[236:239], v161 offset:4416
	v_mul_f32_e32 v212, v48, v164
	v_mul_f32_e32 v213, v49, v165
	v_mul_f32_e32 v214, v50, v244
	v_mul_f32_e32 v215, v51, v245
	s_waitcnt lgkmcnt(1)
	v_add_f32_e32 v164, v158, v250
	v_add_f32_e32 v165, v158, v251
	v_add_f32_e32 v244, v158, v252
	v_add_f32_e32 v245, v158, v253
	v_exp_f32_e32 v164, v164
	v_exp_f32_e32 v165, v165
	v_exp_f32_e32 v244, v244
	v_exp_f32_e32 v245, v245
	ds_read_b128 v[250:253], v161 offset:4448
	v_mul_f32_e32 v216, v52, v164
	v_mul_f32_e32 v217, v53, v165
	v_mul_f32_e32 v218, v54, v244
	v_mul_f32_e32 v219, v55, v245
	s_waitcnt vmcnt(14)
; #define LAS __attribute__((address_space(3)))
; __device__ __forceinline__ float bflo(unsigned u) { return __uint_as_float(u << 16); }
; __device__ __forceinline__ float bfhi(unsigned u) { return __uint_as_float(u & 0xffff0000u); }
; __device__ __forceinline__ f32x16 mfma32(bf16x8 a, bf16x8 b, f32x16 c) { return __builtin_amdgcn_mfma_f32_32x32x16_bf16(a, b, c, 0, 0, 0); }
; __device__ __forceinline__ void phase_ssd_y(const PT& p, LAS unsigned char* lds, int tid, int lane, int wave) {
;     ...
;             for (int sb = 0; sb < 4; ++sb) {
;                 if (sb <= lb) {
;                     f32x16 mm;
; #pragma unroll
;                     for (int qd = 0; qd < 4; ++qd) {
;                         const int s0 = sb * 32 + 8 * qd + 4 * h;
;                         const f32x4 as = *(const LAS f32x4*)(acum + r * 128 + s0), ds = *(const LAS f32x4*)(dtt + r * 128 + s0);
; #pragma unroll
;                         for (int j = 0; j < 4; ++j) { const float v = X[sb][4 * qd + j] * __expf(al - as[j]) * ds[j]; mm[4 * qd + j] = (s0 + j < l) ? v : ((s0 + j == l) ? v + dsk : 0.f); }
;                     }
; #pragma unroll
;                     for (int s2 = 0; s2 < 2; ++s2) acc = mfma32(ld_frag8x2(xrow + sb * 32 + 16 * s2), pack_frag(mm, s2), acc);
;                 }
;             }
; #pragma unroll
;             for (int qd = 0; qd < 4; ++qd) {
;                 LAS u32x2* yp = (LAS u32x2*)(tile + l * SY_TP + (r * 64 + pb * 32 + 8 * qd + 4 * h) * 2); const u32x2 zz = *yp;
;                 const float y0 = acc[4 * qd] * bflo(zz.x), y1 = acc[4 * qd + 1] * bfhi(zz.x);
;                 const float y2 = acc[4 * qd + 2] * bflo(zz.y), y3 = acc[4 * qd + 3] * bfhi(zz.y);
;                 ssq += (y0 * y0 + y1 * y1) + (y2 * y2 + y3 * y3);
;                 u32x2 w; w.x = pk2(y0, y1); w.y = pk2(y2, y3); *yp = w;
;             }
	v_add_f32_e32 v169, v212, v159
	v_add_f32_e32 v183, v213, v159
	v_cmp_eq_u32_e32 vcc, 0, v160
	v_cmp_eq_u32_e64 s[100:101], 1, v160
	s_nop 0
	v_cndmask_b32_e32 v169, 0, v169, vcc
	v_cndmask_b32_e64 v183, 0, v183, s[100:101]
	v_cmp_lt_i32_e32 vcc, 0, v160
	v_cmp_lt_i32_e64 s[100:101], 1, v160
	s_nop 0
	v_cndmask_b32_e32 v212, v169, v212, vcc
	v_cndmask_b32_e64 v213, v183, v213, s[100:101]
	v_add_f32_e32 v169, v214, v159
	v_add_f32_e32 v183, v215, v159
	v_cmp_eq_u32_e32 vcc, 2, v160
	v_cmp_eq_u32_e64 s[100:101], 3, v160
	s_nop 0
	v_cndmask_b32_e32 v169, 0, v169, vcc
	v_cndmask_b32_e64 v183, 0, v183, s[100:101]
	v_cmp_lt_i32_e32 vcc, 2, v160
	v_cmp_lt_i32_e64 s[100:101], 3, v160
	s_nop 0
	v_cndmask_b32_e32 v214, v169, v214, vcc
	v_cndmask_b32_e64 v215, v183, v215, s[100:101]
	v_add_f32_e32 v169, v216, v159
	v_add_f32_e32 v183, v217, v159
	v_cmp_eq_u32_e32 vcc, 8, v160
	v_cmp_eq_u32_e64 s[100:101], 9, v160
	s_nop 0
	v_cndmask_b32_e32 v169, 0, v169, vcc
	v_cndmask_b32_e64 v183, 0, v183, s[100:101]
	v_cmp_lt_i32_e32 vcc, 8, v160
	v_cmp_lt_i32_e64 s[100:101], 9, v160
	s_nop 0
	v_cndmask_b32_e32 v216, v169, v216, vcc
	v_cndmask_b32_e64 v217, v183, v217, s[100:101]
	v_add_f32_e32 v169, v218, v159
	v_add_f32_e32 v183, v219, v159
	v_cmp_eq_u32_e32 vcc, 10, v160
	v_cmp_eq_u32_e64 s[100:101], 11, v160
	s_nop 0
	v_cndmask_b32_e32 v169, 0, v169, vcc
	v_cndmask_b32_e64 v183, 0, v183, s[100:101]
	v_cmp_lt_i32_e32 vcc, 10, v160
	v_cmp_lt_i32_e64 s[100:101], 11, v160
	s_nop 0
	v_cndmask_b32_e32 v218, v169, v218, vcc
	v_cndmask_b32_e64 v219, v183, v219, s[100:101]
	v_cvt_pk_bf16_f32 v212, v212, v213
	v_cvt_pk_bf16_f32 v213, v214, v215
	v_cvt_pk_bf16_f32 v214, v216, v217
	v_cvt_pk_bf16_f32 v215, v218, v219
	s_nop 0
	s_waitcnt vmcnt(12)
	v_permlane32_swap_b32_e32 v112, v114
	v_permlane32_swap_b32_e32 v113, v115
	v_permlane32_swap_b32_e32 v202, v204
	v_permlane32_swap_b32_e32 v203, v205
	s_nop 1
	v_mfma_f32_32x32x16_bf16 v[64:79], v[112:115], v[212:215], v[64:79]
	s_waitcnt lgkmcnt(1)
	v_add_f32_e32 v164, v158, v236
	v_add_f32_e32 v165, v158, v237
	v_add_f32_e32 v244, v158, v238
	v_add_f32_e32 v245, v158, v239
	v_exp_f32_e32 v164, v164
	v_exp_f32_e32 v165, v165
	v_exp_f32_e32 v244, v244
	v_exp_f32_e32 v245, v245
	v_mul_f32_e32 v212, v56, v164
	v_mul_f32_e32 v213, v57, v165
	v_mul_f32_e32 v214, v58, v244
	v_mul_f32_e32 v215, v59, v245
	s_waitcnt lgkmcnt(0)
	v_add_f32_e32 v164, v158, v250
	v_add_f32_e32 v165, v158, v251
	v_add_f32_e32 v244, v158, v252
	v_add_f32_e32 v245, v158, v253
	v_exp_f32_e32 v164, v164
	v_exp_f32_e32 v165, v165
	v_exp_f32_e32 v244, v244
	v_exp_f32_e32 v245, v245
	v_mul_f32_e32 v216, v60, v164
	v_mul_f32_e32 v217, v61, v165
	v_mul_f32_e32 v218, v62, v244
	v_mul_f32_e32 v219, v63, v245
	v_add_f32_e32 v169, v212, v159
	v_add_f32_e32 v183, v213, v159
	v_cmp_eq_u32_e32 vcc, 16, v160
	v_cmp_eq_u32_e64 s[100:101], 17, v160
	s_nop 0
	v_cndmask_b32_e32 v169, 0, v169, vcc
	v_cndmask_b32_e64 v183, 0, v183, s[100:101]
	v_cmp_lt_i32_e32 vcc, 16, v160
	v_cmp_lt_i32_e64 s[100:101], 17, v160
	s_nop 0
	v_cndmask_b32_e32 v212, v169, v212, vcc
	v_cndmask_b32_e64 v213, v183, v213, s[100:101]
	v_add_f32_e32 v169, v214, v159
	v_add_f32_e32 v183, v215, v159
	v_cmp_eq_u32_e32 vcc, 18, v160
	v_cmp_eq_u32_e64 s[100:101], 19, v160
	s_nop 0
	v_cndmask_b32_e32 v169, 0, v169, vcc
	v_cndmask_b32_e64 v183, 0, v183, s[100:101]
	v_cmp_lt_i32_e32 vcc, 18, v160
	v_cmp_lt_i32_e64 s[100:101], 19, v160
	s_nop 0
	v_cndmask_b32_e32 v214, v169, v214, vcc
	v_cndmask_b32_e64 v215, v183, v215, s[100:101]
	v_add_f32_e32 v169, v216, v159
	v_add_f32_e32 v183, v217, v159
	v_cmp_eq_u32_e32 vcc, 24, v160
	v_cmp_eq_u32_e64 s[100:101], 25, v160
	s_nop 0
	v_cndmask_b32_e32 v169, 0, v169, vcc
	v_cndmask_b32_e64 v183, 0, v183, s[100:101]
	v_cmp_lt_i32_e32 vcc, 24, v160
	v_cmp_lt_i32_e64 s[100:101], 25, v160
	s_nop 0
	v_cndmask_b32_e32 v216, v169, v216, vcc
	v_cndmask_b32_e64 v217, v183, v217, s[100:101]
	v_add_f32_e32 v169, v218, v159
	v_add_f32_e32 v183, v219, v159
	v_cmp_eq_u32_e32 vcc, 26, v160
	v_cmp_eq_u32_e64 s[100:101], 27, v160
	s_nop 0
	v_cndmask_b32_e32 v169, 0, v169, vcc
	v_cndmask_b32_e64 v183, 0, v183, s[100:101]
	v_cmp_lt_i32_e32 vcc, 26, v160
	v_cmp_lt_i32_e64 s[100:101], 27, v160
	s_nop 0
	v_cndmask_b32_e32 v218, v169, v218, vcc
	v_cndmask_b32_e64 v219, v183, v219, s[100:101]
	s_cmp_eq_u32 s94, 0x1c000
	s_cselect_b32 s100, 0, 4
	s_add_u32 s84, s84, s100
	s_addc_u32 s85, s85, 0
	v_mov_b32_e32 v164, 0
	global_load_dword v159, v164, s[84:85]
	v_cvt_pk_bf16_f32 v212, v212, v213
	v_cvt_pk_bf16_f32 v213, v214, v215
	v_cvt_pk_bf16_f32 v214, v216, v217
	v_cvt_pk_bf16_f32 v215, v218, v219
	s_nop 0
	s_nop 0
	v_mfma_f32_32x32x16_bf16 v[64:79], v[202:205], v[212:215], v[64:79]
	global_load_dwordx4 v[112:115], v[184:185], off offset:128
	global_load_dwordx4 v[202:205], v[184:185], off offset:160
	s_nop 10
	ds_read_b64 v[216:217], v162 offset:0
	s_waitcnt lgkmcnt(0)
	v_lshlrev_b32_e32 v169, 16, v216
	v_and_b32_e32 v183, 0xffff0000, v216
	v_lshlrev_b32_e32 v254, 16, v217
	v_and_b32_e32 v255, 0xffff0000, v217
	v_mul_f32_e32 v169, v64, v169
	v_mul_f32_e32 v183, v65, v183
	v_mul_f32_e32 v254, v66, v254
	v_mul_f32_e32 v255, v67, v255
	v_mul_f32_e32 v164, v169, v169
	v_mul_f32_e32 v165, v254, v254
	v_fmac_f32_e32 v164, v183, v183
	v_fmac_f32_e32 v165, v255, v255
	v_cvt_pk_bf16_f32 v216, v169, v183
	v_cvt_pk_bf16_f32 v217, v254, v255
	v_add_f32_e32 v164, v164, v165
	ds_write_b64 v162, v[216:217] offset:0
	v_add_f32_e32 v126, v126, v164
	ds_read_b64 v[216:217], v162 offset:16
	s_waitcnt lgkmcnt(0)
; #define LAS __attribute__((address_space(3)))
; __device__ __forceinline__ float bflo(unsigned u) { return __uint_as_float(u << 16); }
; __device__ __forceinline__ float bfhi(unsigned u) { return __uint_as_float(u & 0xffff0000u); }
; __device__ __forceinline__ f32x16 mfma32(bf16x8 a, bf16x8 b, f32x16 c) { return __builtin_amdgcn_mfma_f32_32x32x16_bf16(a, b, c, 0, 0, 0); }
; __device__ __forceinline__ void phase_ssd_y(const PT& p, LAS unsigned char* lds, int tid, int lane, int wave) {
;     ...
;             const bf16* pp = PV + ((size_t)(bc * 32 + hh) * 64 + pb * 32 + r32) * 128 + 8 * h;
; #pragma unroll
;             for (int st = 0; st < 8; ++st) acc = mfma32(ld_frag16(pp + 16 * st), cf[st], acc);
;             const float al = acum[r * 128 + l]; const float el = __expf(al); const float dsk = p.in[11][hh];
; #pragma unroll
;             for (int i = 0; i < 16; ++i) acc[i] *= el;
;     ...
;             for (int qd = 0; qd < 4; ++qd) {
;                 LAS u32x2* yp = (LAS u32x2*)(tile + l * SY_TP + (r * 64 + pb * 32 + 8 * qd + 4 * h) * 2); const u32x2 zz = *yp;
;                 const float y0 = acc[4 * qd] * bflo(zz.x), y1 = acc[4 * qd + 1] * bfhi(zz.x);
;                 const float y2 = acc[4 * qd + 2] * bflo(zz.y), y3 = acc[4 * qd + 3] * bfhi(zz.y);
;                 ssq += (y0 * y0 + y1 * y1) + (y2 * y2 + y3 * y3);
;                 u32x2 w; w.x = pk2(y0, y1); w.y = pk2(y2, y3); *yp = w;
;             }
	v_lshlrev_b32_e32 v169, 16, v216
	v_and_b32_e32 v183, 0xffff0000, v216
	v_lshlrev_b32_e32 v254, 16, v217
	v_and_b32_e32 v255, 0xffff0000, v217
	v_mul_f32_e32 v169, v68, v169
	v_mul_f32_e32 v183, v69, v183
	v_mul_f32_e32 v254, v70, v254
	v_mul_f32_e32 v255, v71, v255
	v_mul_f32_e32 v164, v169, v169
	v_mul_f32_e32 v165, v254, v254
	v_fmac_f32_e32 v164, v183, v183
	v_fmac_f32_e32 v165, v255, v255
	v_cvt_pk_bf16_f32 v216, v169, v183
	v_cvt_pk_bf16_f32 v217, v254, v255
	v_add_f32_e32 v164, v164, v165
	ds_write_b64 v162, v[216:217] offset:16
	v_add_f32_e32 v126, v126, v164
	ds_read_b64 v[216:217], v162 offset:32
	s_waitcnt lgkmcnt(0)
	v_lshlrev_b32_e32 v169, 16, v216
	v_and_b32_e32 v183, 0xffff0000, v216
	v_lshlrev_b32_e32 v254, 16, v217
	v_and_b32_e32 v255, 0xffff0000, v217
	v_mul_f32_e32 v169, v72, v169
	v_mul_f32_e32 v183, v73, v183
	v_mul_f32_e32 v254, v74, v254
	v_mul_f32_e32 v255, v75, v255
	v_mul_f32_e32 v164, v169, v169
	v_mul_f32_e32 v165, v254, v254
	v_fmac_f32_e32 v164, v183, v183
	v_fmac_f32_e32 v165, v255, v255
	v_cvt_pk_bf16_f32 v216, v169, v183
	v_cvt_pk_bf16_f32 v217, v254, v255
	v_add_f32_e32 v164, v164, v165
	ds_write_b64 v162, v[216:217] offset:32
	v_add_f32_e32 v126, v126, v164
	ds_read_b64 v[216:217], v162 offset:48
	s_waitcnt lgkmcnt(0)
	v_lshlrev_b32_e32 v169, 16, v216
	v_and_b32_e32 v183, 0xffff0000, v216
	v_lshlrev_b32_e32 v254, 16, v217
	v_and_b32_e32 v255, 0xffff0000, v217
	v_mul_f32_e32 v169, v76, v169
	v_mul_f32_e32 v183, v77, v183
	v_mul_f32_e32 v254, v78, v254
	v_mul_f32_e32 v255, v79, v255
	v_mul_f32_e32 v164, v169, v169
	v_mul_f32_e32 v165, v254, v254
	v_fmac_f32_e32 v164, v183, v183
	v_fmac_f32_e32 v165, v255, v255
	v_cvt_pk_bf16_f32 v216, v169, v183
	v_cvt_pk_bf16_f32 v217, v254, v255
	v_add_f32_e32 v164, v164, v165
	ds_write_b64 v162, v[216:217] offset:48
	v_add_f32_e32 v126, v126, v164
	v_add_u32_e32 v161, 0x200, v161
	v_add_u32_e32 v141, 0x200, v141
	v_add_u32_e32 v162, 0x80, v162
	v_mov_b32_e32 v206, v184
	v_mov_b32_e32 v207, v185
	v_add_co_u32_e32 v184, vcc, 0x4000, v184
	s_nop 1
	v_addc_co_u32_e32 v185, vcc, 0, v185, vcc
	s_add_u32 s94, s94, 0x4000
	s_cmp_eq_u32 s94, 0x20000
	s_cbranch_scc0 .Lp5v2_head
	s_branch .Lp5v_exit
.Lp5v1:
	v_lshl_add_u64 v[212:213], v[142:143], 0, s[94:95]
	v_lshl_add_u64 v[206:207], v[144:145], 0, s[94:95]
	v_mov_b32_e32 v164, 0
	v_add_co_u32_e32 v206, vcc, 0x1a900000, v206
	s_nop 1
	v_addc_co_u32_e32 v207, vcc, 0, v207, vcc
	v_bfe_u32 v164, v117, 5, 1
	v_lshlrev_b32_e32 v164, 3, v164
	v_add_co_u32_e32 v206, vcc, v164, v206
	s_nop 1
	v_addc_co_u32_e32 v207, vcc, 0, v207, vcc
	v_mov_b32_e32 v164, 0
	v_add_co_u32_e32 v184, vcc, 0x4000, v206
	s_nop 1
	v_addc_co_u32_e32 v185, vcc, 0, v207, vcc
	global_load_dword v159, v164, s[84:85]
	global_load_dwordx4 v[170:173], v[212:213], off
	global_load_dwordx4 v[174:177], v[212:213], off offset:32
	global_load_dwordx4 v[178:181], v[212:213], off offset:64
	global_load_dwordx4 v[220:223], v[212:213], off offset:96
	global_load_dwordx4 v[224:227], v[212:213], off offset:128
	global_load_dwordx4 v[228:231], v[212:213], off offset:160
	global_load_dwordx4 v[232:235], v[212:213], off offset:192
	global_load_dwordx4 v[208:211], v[212:213], off offset:224
	global_load_dwordx4 v[150:153], v[206:207], off offset:0
	global_load_dwordx4 v[154:157], v[206:207], off offset:32
	global_load_dwordx4 v[192:195], v[206:207], off offset:64
	global_load_dwordx4 v[198:201], v[206:207], off offset:96
	s_waitcnt vmcnt(0)
.Lp5v1_head:
	s_add_u32 s100, s94, 0x4000
	s_mov_b32 s101, 0
	ds_read_b32 v158, v141
	v_lshl_add_u64 v[212:213], v[142:143], 0, s[100:101]
	s_waitcnt vmcnt(12)
	v_mfma_f32_32x32x16_bf16 v[64:79], v[170:173], v[80:83], 0
	global_load_dwordx4 v[170:173], v[212:213], off
	s_waitcnt vmcnt(12)
	v_mfma_f32_32x32x16_bf16 v[64:79], v[174:177], v[84:87], v[64:79]
	global_load_dwordx4 v[174:177], v[212:213], off offset:32
	s_waitcnt vmcnt(12)
	v_mfma_f32_32x32x16_bf16 v[64:79], v[178:181], v[88:91], v[64:79]
	global_load_dwordx4 v[178:181], v[212:213], off offset:64
	s_waitcnt vmcnt(12)
	v_mfma_f32_32x32x16_bf16 v[64:79], v[220:223], v[92:95], v[64:79]
	global_load_dwordx4 v[220:223], v[212:213], off offset:96
	s_waitcnt vmcnt(12)
	v_mfma_f32_32x32x16_bf16 v[64:79], v[224:227], v[96:99], v[64:79]
	global_load_dwordx4 v[224:227], v[212:213], off offset:128
	s_waitcnt vmcnt(12)
	v_mfma_f32_32x32x16_bf16 v[64:79], v[228:231], v[100:103], v[64:79]
	global_load_dwordx4 v[228:231], v[212:213], off offset:160
	s_waitcnt vmcnt(12)
	v_mfma_f32_32x32x16_bf16 v[64:79], v[232:235], v[104:107], v[64:79]
	global_load_dwordx4 v[232:235], v[212:213], off offset:192
	s_waitcnt vmcnt(12)
	v_mfma_f32_32x32x16_bf16 v[64:79], v[208:211], v[108:111], v[64:79]
	global_load_dwordx4 v[208:211], v[212:213], off offset:224
	s_waitcnt lgkmcnt(0)
	v_mul_f32_e32 v164, 0x3fb8aa3b, v158
	v_exp_f32_e32 v165, v164
	v_mov_b32_e32 v158, v164
	s_nop 8
	v_mul_f32_e32 v64, v165, v64
	v_mul_f32_e32 v65, v165, v65
	v_mul_f32_e32 v66, v165, v66
	v_mul_f32_e32 v67, v165, v67
	v_mul_f32_e32 v68, v165, v68
	v_mul_f32_e32 v69, v165, v69
	v_mul_f32_e32 v70, v165, v70
	v_mul_f32_e32 v71, v165, v71
	v_mul_f32_e32 v72, v165, v72
	v_mul_f32_e32 v73, v165, v73
	v_mul_f32_e32 v74, v165, v74
	v_mul_f32_e32 v75, v165, v75
	v_mul_f32_e32 v76, v165, v76
	v_mul_f32_e32 v77, v165, v77
	v_mul_f32_e32 v78, v165, v78
	v_mul_f32_e32 v79, v165, v79
	ds_read_b128 v[236:239], v161 offset:4096
	ds_read_b128 v[250:253], v161 offset:4128
	s_waitcnt lgkmcnt(1)
; #define LAS __attribute__((address_space(3)))
; __device__ __forceinline__ f32x16 mfma32(bf16x8 a, bf16x8 b, f32x16 c) { return __builtin_amdgcn_mfma_f32_32x32x16_bf16(a, b, c, 0, 0, 0); }
; __device__ __forceinline__ void phase_ssd_y(const PT& p, LAS unsigned char* lds, int tid, int lane, int wave) {
;     ...
;             for (int sb = 0; sb < 4; ++sb) {
;                 if (sb <= lb) {
;                     f32x16 mm;
; #pragma unroll
;                     for (int qd = 0; qd < 4; ++qd) {
;                         const int s0 = sb * 32 + 8 * qd + 4 * h;
;                         const f32x4 as = *(const LAS f32x4*)(acum + r * 128 + s0), ds = *(const LAS f32x4*)(dtt + r * 128 + s0);
; #pragma unroll
;                         for (int j = 0; j < 4; ++j) { const float v = X[sb][4 * qd + j] * __expf(al - as[j]) * ds[j]; mm[4 * qd + j] = (s0 + j < l) ? v : ((s0 + j == l) ? v + dsk : 0.f); }
;                     }
; #pragma unroll
;                     for (int s2 = 0; s2 < 2; ++s2) acc = mfma32(ld_frag8x2(xrow + sb * 32 + 16 * s2), pack_frag(mm, s2), acc);
	v_add_f32_e32 v164, v158, v236
	v_add_f32_e32 v165, v158, v237
	v_add_f32_e32 v244, v158, v238
	v_add_f32_e32 v245, v158, v239
	v_exp_f32_e32 v164, v164
	v_exp_f32_e32 v165, v165
	v_exp_f32_e32 v244, v244
	v_exp_f32_e32 v245, v245
	ds_read_b128 v[236:239], v161 offset:4160
	v_mul_f32_e32 v212, v0, v164
	v_mul_f32_e32 v213, v1, v165
	v_mul_f32_e32 v214, v2, v244
	v_mul_f32_e32 v215, v3, v245
	s_waitcnt lgkmcnt(1)
	v_add_f32_e32 v164, v158, v250
	v_add_f32_e32 v165, v158, v251
	v_add_f32_e32 v244, v158, v252
	v_add_f32_e32 v245, v158, v253
	v_exp_f32_e32 v164, v164
	v_exp_f32_e32 v165, v165
	v_exp_f32_e32 v244, v244
	v_exp_f32_e32 v245, v245
	ds_read_b128 v[250:253], v161 offset:4192
	v_mul_f32_e32 v216, v4, v164
	v_mul_f32_e32 v217, v5, v165
	v_mul_f32_e32 v218, v6, v244
	v_mul_f32_e32 v219, v7, v245
	v_cvt_pk_bf16_f32 v212, v212, v213
	v_cvt_pk_bf16_f32 v213, v214, v215
	v_cvt_pk_bf16_f32 v214, v216, v217
	v_cvt_pk_bf16_f32 v215, v218, v219
	s_nop 0
	s_waitcnt vmcnt(11)
	v_permlane32_swap_b32_e32 v150, v152
	v_permlane32_swap_b32_e32 v151, v153
	v_permlane32_swap_b32_e32 v154, v156
	v_permlane32_swap_b32_e32 v155, v157
	s_nop 1
	v_mfma_f32_32x32x16_bf16 v[64:79], v[150:153], v[212:215], v[64:79]
	s_waitcnt lgkmcnt(1)
	v_add_f32_e32 v164, v158, v236
	v_add_f32_e32 v165, v158, v237
	v_add_f32_e32 v244, v158, v238
	v_add_f32_e32 v245, v158, v239
	v_exp_f32_e32 v164, v164
	v_exp_f32_e32 v165, v165
	v_exp_f32_e32 v244, v244
	v_exp_f32_e32 v245, v245
	v_mul_f32_e32 v212, v8, v164
	v_mul_f32_e32 v213, v9, v165
	v_mul_f32_e32 v214, v10, v244
	v_mul_f32_e32 v215, v11, v245
	s_waitcnt lgkmcnt(0)
	v_add_f32_e32 v164, v158, v250
	v_add_f32_e32 v165, v158, v251
	v_add_f32_e32 v244, v158, v252
	v_add_f32_e32 v245, v158, v253
	v_exp_f32_e32 v164, v164
	v_exp_f32_e32 v165, v165
	v_exp_f32_e32 v244, v244
	v_exp_f32_e32 v245, v245
	v_mul_f32_e32 v216, v12, v164
	v_mul_f32_e32 v217, v13, v165
	v_mul_f32_e32 v218, v14, v244
	v_mul_f32_e32 v219, v15, v245
	v_cvt_pk_bf16_f32 v212, v212, v213
	v_cvt_pk_bf16_f32 v213, v214, v215
	v_cvt_pk_bf16_f32 v214, v216, v217
	v_cvt_pk_bf16_f32 v215, v218, v219
	s_nop 0
	s_nop 0
	v_mfma_f32_32x32x16_bf16 v[64:79], v[154:157], v[212:215], v[64:79]
	global_load_dwordx4 v[150:153], v[184:185], off offset:0
	global_load_dwordx4 v[154:157], v[184:185], off offset:32
	ds_read_b128 v[236:239], v161 offset:4224
	ds_read_b128 v[250:253], v161 offset:4256
	s_waitcnt lgkmcnt(1)
	v_add_f32_e32 v164, v158, v236
	v_add_f32_e32 v165, v158, v237
	v_add_f32_e32 v244, v158, v238
	v_add_f32_e32 v245, v158, v239
	v_exp_f32_e32 v164, v164
	v_exp_f32_e32 v165, v165
	v_exp_f32_e32 v244, v244
	v_exp_f32_e32 v245, v245
	ds_read_b128 v[236:239], v161 offset:4288
	v_mul_f32_e32 v212, v16, v164
	v_mul_f32_e32 v213, v17, v165
	v_mul_f32_e32 v214, v18, v244
	v_mul_f32_e32 v215, v19, v245
	s_waitcnt lgkmcnt(1)
	v_add_f32_e32 v164, v158, v250
	v_add_f32_e32 v165, v158, v251
	v_add_f32_e32 v244, v158, v252
	v_add_f32_e32 v245, v158, v253
	v_exp_f32_e32 v164, v164
	v_exp_f32_e32 v165, v165
	v_exp_f32_e32 v244, v244
	v_exp_f32_e32 v245, v245
	ds_read_b128 v[250:253], v161 offset:4320
	v_mul_f32_e32 v216, v20, v164
	v_mul_f32_e32 v217, v21, v165
	v_mul_f32_e32 v218, v22, v244
	v_mul_f32_e32 v219, v23, v245
	s_waitcnt vmcnt(12)
	v_add_f32_e32 v169, v212, v159
	v_add_f32_e32 v183, v213, v159
	v_cmp_eq_u32_e32 vcc, 0, v160
	v_cmp_eq_u32_e64 s[100:101], 1, v160
	s_nop 0
	v_cndmask_b32_e32 v169, 0, v169, vcc
	v_cndmask_b32_e64 v183, 0, v183, s[100:101]
	v_cmp_lt_i32_e32 vcc, 0, v160
	v_cmp_lt_i32_e64 s[100:101], 1, v160
	s_nop 0
	v_cndmask_b32_e32 v212, v169, v212, vcc
	v_cndmask_b32_e64 v213, v183, v213, s[100:101]
	v_add_f32_e32 v169, v214, v159
	v_add_f32_e32 v183, v215, v159
	v_cmp_eq_u32_e32 vcc, 2, v160
	v_cmp_eq_u32_e64 s[100:101], 3, v160
	s_nop 0
	v_cndmask_b32_e32 v169, 0, v169, vcc
	v_cndmask_b32_e64 v183, 0, v183, s[100:101]
	v_cmp_lt_i32_e32 vcc, 2, v160
	v_cmp_lt_i32_e64 s[100:101], 3, v160
	s_nop 0
	v_cndmask_b32_e32 v214, v169, v214, vcc
	v_cndmask_b32_e64 v215, v183, v215, s[100:101]
	v_add_f32_e32 v169, v216, v159
	v_add_f32_e32 v183, v217, v159
	v_cmp_eq_u32_e32 vcc, 8, v160
	v_cmp_eq_u32_e64 s[100:101], 9, v160
	s_nop 0
	v_cndmask_b32_e32 v169, 0, v169, vcc
	v_cndmask_b32_e64 v183, 0, v183, s[100:101]
	v_cmp_lt_i32_e32 vcc, 8, v160
	v_cmp_lt_i32_e64 s[100:101], 9, v160
	s_nop 0
	v_cndmask_b32_e32 v216, v169, v216, vcc
	v_cndmask_b32_e64 v217, v183, v217, s[100:101]
	v_add_f32_e32 v169, v218, v159
	v_add_f32_e32 v183, v219, v159
	v_cmp_eq_u32_e32 vcc, 10, v160
	v_cmp_eq_u32_e64 s[100:101], 11, v160
	s_nop 0
	v_cndmask_b32_e32 v169, 0, v169, vcc
	v_cndmask_b32_e64 v183, 0, v183, s[100:101]
	v_cmp_lt_i32_e32 vcc, 10, v160
	v_cmp_lt_i32_e64 s[100:101], 11, v160
	s_nop 0
	v_cndmask_b32_e32 v218, v169, v218, vcc
	v_cndmask_b32_e64 v219, v183, v219, s[100:101]
	v_cvt_pk_bf16_f32 v212, v212, v213
	v_cvt_pk_bf16_f32 v213, v214, v215
	v_cvt_pk_bf16_f32 v214, v216, v217
	v_cvt_pk_bf16_f32 v215, v218, v219
	s_nop 0
	s_waitcnt vmcnt(10)
	v_permlane32_swap_b32_e32 v192, v194
	v_permlane32_swap_b32_e32 v193, v195
	v_permlane32_swap_b32_e32 v198, v200
	v_permlane32_swap_b32_e32 v199, v201
	s_nop 1
	v_mfma_f32_32x32x16_bf16 v[64:79], v[192:195], v[212:215], v[64:79]
	s_waitcnt lgkmcnt(1)
	v_add_f32_e32 v164, v158, v236
	v_add_f32_e32 v165, v158, v237
	v_add_f32_e32 v244, v158, v238
	v_add_f32_e32 v245, v158, v239
	v_exp_f32_e32 v164, v164
	v_exp_f32_e32 v165, v165
	v_exp_f32_e32 v244, v244
	v_exp_f32_e32 v245, v245
	v_mul_f32_e32 v212, v24, v164
	v_mul_f32_e32 v213, v25, v165
	v_mul_f32_e32 v214, v26, v244
	v_mul_f32_e32 v215, v27, v245
	s_waitcnt lgkmcnt(0)
; #define LAS __attribute__((address_space(3)))
; __device__ __forceinline__ float bflo(unsigned u) { return __uint_as_float(u << 16); }
; __device__ __forceinline__ float bfhi(unsigned u) { return __uint_as_float(u & 0xffff0000u); }
; __device__ __forceinline__ f32x16 mfma32(bf16x8 a, bf16x8 b, f32x16 c) { return __builtin_amdgcn_mfma_f32_32x32x16_bf16(a, b, c, 0, 0, 0); }
; __device__ __forceinline__ void phase_ssd_y(const PT& p, LAS unsigned char* lds, int tid, int lane, int wave) {
;     ...
;                     for (int qd = 0; qd < 4; ++qd) {
;                         const int s0 = sb * 32 + 8 * qd + 4 * h;
;                         const f32x4 as = *(const LAS f32x4*)(acum + r * 128 + s0), ds = *(const LAS f32x4*)(dtt + r * 128 + s0);
; #pragma unroll
;                         for (int j = 0; j < 4; ++j) { const float v = X[sb][4 * qd + j] * __expf(al - as[j]) * ds[j]; mm[4 * qd + j] = (s0 + j < l) ? v : ((s0 + j == l) ? v + dsk : 0.f); }
;                     }
; #pragma unroll
;                     for (int s2 = 0; s2 < 2; ++s2) acc = mfma32(ld_frag8x2(xrow + sb * 32 + 16 * s2), pack_frag(mm, s2), acc);
;                 }
;             }
; #pragma unroll
;             for (int qd = 0; qd < 4; ++qd) {
;                 LAS u32x2* yp = (LAS u32x2*)(tile + l * SY_TP + (r * 64 + pb * 32 + 8 * qd + 4 * h) * 2); const u32x2 zz = *yp;
;                 const float y0 = acc[4 * qd] * bflo(zz.x), y1 = acc[4 * qd + 1] * bfhi(zz.x);
;                 const float y2 = acc[4 * qd + 2] * bflo(zz.y), y3 = acc[4 * qd + 3] * bfhi(zz.y);
;                 ssq += (y0 * y0 + y1 * y1) + (y2 * y2 + y3 * y3);
;                 u32x2 w; w.x = pk2(y0, y1); w.y = pk2(y2, y3); *yp = w;
;             }
	v_add_f32_e32 v164, v158, v250
	v_add_f32_e32 v165, v158, v251
	v_add_f32_e32 v244, v158, v252
	v_add_f32_e32 v245, v158, v253
	v_exp_f32_e32 v164, v164
	v_exp_f32_e32 v165, v165
	v_exp_f32_e32 v244, v244
	v_exp_f32_e32 v245, v245
	v_mul_f32_e32 v216, v28, v164
	v_mul_f32_e32 v217, v29, v165
	v_mul_f32_e32 v218, v30, v244
	v_mul_f32_e32 v219, v31, v245
	v_add_f32_e32 v169, v212, v159
	v_add_f32_e32 v183, v213, v159
	v_cmp_eq_u32_e32 vcc, 16, v160
	v_cmp_eq_u32_e64 s[100:101], 17, v160
	s_nop 0
	v_cndmask_b32_e32 v169, 0, v169, vcc
	v_cndmask_b32_e64 v183, 0, v183, s[100:101]
	v_cmp_lt_i32_e32 vcc, 16, v160
	v_cmp_lt_i32_e64 s[100:101], 17, v160
	s_nop 0
	v_cndmask_b32_e32 v212, v169, v212, vcc
	v_cndmask_b32_e64 v213, v183, v213, s[100:101]
	v_add_f32_e32 v169, v214, v159
	v_add_f32_e32 v183, v215, v159
	v_cmp_eq_u32_e32 vcc, 18, v160
	v_cmp_eq_u32_e64 s[100:101], 19, v160
	s_nop 0
	v_cndmask_b32_e32 v169, 0, v169, vcc
	v_cndmask_b32_e64 v183, 0, v183, s[100:101]
	v_cmp_lt_i32_e32 vcc, 18, v160
	v_cmp_lt_i32_e64 s[100:101], 19, v160
	s_nop 0
	v_cndmask_b32_e32 v214, v169, v214, vcc
	v_cndmask_b32_e64 v215, v183, v215, s[100:101]
	v_add_f32_e32 v169, v216, v159
	v_add_f32_e32 v183, v217, v159
	v_cmp_eq_u32_e32 vcc, 24, v160
	v_cmp_eq_u32_e64 s[100:101], 25, v160
	s_nop 0
	v_cndmask_b32_e32 v169, 0, v169, vcc
	v_cndmask_b32_e64 v183, 0, v183, s[100:101]
	v_cmp_lt_i32_e32 vcc, 24, v160
	v_cmp_lt_i32_e64 s[100:101], 25, v160
	s_nop 0
	v_cndmask_b32_e32 v216, v169, v216, vcc
	v_cndmask_b32_e64 v217, v183, v217, s[100:101]
	v_add_f32_e32 v169, v218, v159
	v_add_f32_e32 v183, v219, v159
	v_cmp_eq_u32_e32 vcc, 26, v160
	v_cmp_eq_u32_e64 s[100:101], 27, v160
	s_nop 0
	v_cndmask_b32_e32 v169, 0, v169, vcc
	v_cndmask_b32_e64 v183, 0, v183, s[100:101]
	v_cmp_lt_i32_e32 vcc, 26, v160
	v_cmp_lt_i32_e64 s[100:101], 27, v160
	s_nop 0
	v_cndmask_b32_e32 v218, v169, v218, vcc
	v_cndmask_b32_e64 v219, v183, v219, s[100:101]
	s_cmp_eq_u32 s94, 0x1c000
	s_cselect_b32 s100, 0, 4
	s_add_u32 s84, s84, s100
	s_addc_u32 s85, s85, 0
	v_mov_b32_e32 v164, 0
	global_load_dword v159, v164, s[84:85]
	v_cvt_pk_bf16_f32 v212, v212, v213
	v_cvt_pk_bf16_f32 v213, v214, v215
	v_cvt_pk_bf16_f32 v214, v216, v217
	v_cvt_pk_bf16_f32 v215, v218, v219
	s_nop 0
	s_nop 0
	v_mfma_f32_32x32x16_bf16 v[64:79], v[198:201], v[212:215], v[64:79]
	global_load_dwordx4 v[192:195], v[184:185], off offset:64
	global_load_dwordx4 v[198:201], v[184:185], off offset:96
	s_nop 10
	ds_read_b64 v[216:217], v162 offset:0
	s_waitcnt lgkmcnt(0)
	v_lshlrev_b32_e32 v169, 16, v216
	v_and_b32_e32 v183, 0xffff0000, v216
	v_lshlrev_b32_e32 v254, 16, v217
	v_and_b32_e32 v255, 0xffff0000, v217
	v_mul_f32_e32 v169, v64, v169
	v_mul_f32_e32 v183, v65, v183
	v_mul_f32_e32 v254, v66, v254
	v_mul_f32_e32 v255, v67, v255
	v_mul_f32_e32 v164, v169, v169
	v_mul_f32_e32 v165, v254, v254
	v_fmac_f32_e32 v164, v183, v183
	v_fmac_f32_e32 v165, v255, v255
	v_cvt_pk_bf16_f32 v216, v169, v183
	v_cvt_pk_bf16_f32 v217, v254, v255
	v_add_f32_e32 v164, v164, v165
	ds_write_b64 v162, v[216:217] offset:0
	v_add_f32_e32 v126, v126, v164
	ds_read_b64 v[216:217], v162 offset:16
	s_waitcnt lgkmcnt(0)
	v_lshlrev_b32_e32 v169, 16, v216
	v_and_b32_e32 v183, 0xffff0000, v216
	v_lshlrev_b32_e32 v254, 16, v217
	v_and_b32_e32 v255, 0xffff0000, v217
	v_mul_f32_e32 v169, v68, v169
	v_mul_f32_e32 v183, v69, v183
	v_mul_f32_e32 v254, v70, v254
	v_mul_f32_e32 v255, v71, v255
	v_mul_f32_e32 v164, v169, v169
	v_mul_f32_e32 v165, v254, v254
	v_fmac_f32_e32 v164, v183, v183
	v_fmac_f32_e32 v165, v255, v255
	v_cvt_pk_bf16_f32 v216, v169, v183
	v_cvt_pk_bf16_f32 v217, v254, v255
	v_add_f32_e32 v164, v164, v165
	ds_write_b64 v162, v[216:217] offset:16
	v_add_f32_e32 v126, v126, v164
	ds_read_b64 v[216:217], v162 offset:32
	s_waitcnt lgkmcnt(0)
	v_lshlrev_b32_e32 v169, 16, v216
	v_and_b32_e32 v183, 0xffff0000, v216
	v_lshlrev_b32_e32 v254, 16, v217
	v_and_b32_e32 v255, 0xffff0000, v217
	v_mul_f32_e32 v169, v72, v169
	v_mul_f32_e32 v183, v73, v183
	v_mul_f32_e32 v254, v74, v254
	v_mul_f32_e32 v255, v75, v255
	v_mul_f32_e32 v164, v169, v169
	v_mul_f32_e32 v165, v254, v254
	v_fmac_f32_e32 v164, v183, v183
	v_fmac_f32_e32 v165, v255, v255
	v_cvt_pk_bf16_f32 v216, v169, v183
	v_cvt_pk_bf16_f32 v217, v254, v255
	v_add_f32_e32 v164, v164, v165
	ds_write_b64 v162, v[216:217] offset:32
	v_add_f32_e32 v126, v126, v164
	ds_read_b64 v[216:217], v162 offset:48
	s_waitcnt lgkmcnt(0)
	v_lshlrev_b32_e32 v169, 16, v216
	v_and_b32_e32 v183, 0xffff0000, v216
	v_lshlrev_b32_e32 v254, 16, v217
	v_and_b32_e32 v255, 0xffff0000, v217
	v_mul_f32_e32 v169, v76, v169
	v_mul_f32_e32 v183, v77, v183
	v_mul_f32_e32 v254, v78, v254
	v_mul_f32_e32 v255, v79, v255
	v_mul_f32_e32 v164, v169, v169
	v_mul_f32_e32 v165, v254, v254
	v_fmac_f32_e32 v164, v183, v183
	v_fmac_f32_e32 v165, v255, v255
	v_cvt_pk_bf16_f32 v216, v169, v183
	v_cvt_pk_bf16_f32 v217, v254, v255
	v_add_f32_e32 v164, v164, v165
	ds_write_b64 v162, v[216:217] offset:48
	v_add_f32_e32 v126, v126, v164
	v_add_u32_e32 v161, 0x200, v161
	v_add_u32_e32 v141, 0x200, v141
	v_add_u32_e32 v162, 0x80, v162
	v_mov_b32_e32 v206, v184
	v_mov_b32_e32 v207, v185
	v_add_co_u32_e32 v184, vcc, 0x4000, v184
	s_nop 1
	v_addc_co_u32_e32 v185, vcc, 0, v185, vcc
	s_add_u32 s94, s94, 0x4000
	s_cmp_eq_u32 s94, 0x20000
	s_cbranch_scc0 .Lp5v1_head
	s_branch .Lp5v_exit
; #define LAS __attribute__((address_space(3)))
; __device__ __forceinline__ f32x16 mfma32(bf16x8 a, bf16x8 b, f32x16 c) { return __builtin_amdgcn_mfma_f32_32x32x16_bf16(a, b, c, 0, 0, 0); }
; __device__ __forceinline__ void phase_ssd_y(const PT& p, LAS unsigned char* lds, int tid, int lane, int wave) {
;     ...
;             const bf16* pp = PV + ((size_t)(bc * 32 + hh) * 64 + pb * 32 + r32) * 128 + 8 * h;
; #pragma unroll
;             for (int st = 0; st < 8; ++st) acc = mfma32(ld_frag16(pp + 16 * st), cf[st], acc);
;             const float al = acum[r * 128 + l]; const float el = __expf(al); const float dsk = p.in[11][hh];
; #pragma unroll
;             for (int i = 0; i < 16; ++i) acc[i] *= el;
;             const bf16* xrow = xT + ((size_t)bc * 2048 + hh * 64 + pb * 32 + r32) * 128 + 4 * h;
; #pragma unroll
;             for (int sb = 0; sb < 4; ++sb) {
;                 if (sb <= lb) {
;                     f32x16 mm;
; #pragma unroll
;                     for (int qd = 0; qd < 4; ++qd) {
;                         const int s0 = sb * 32 + 8 * qd + 4 * h;
;                         const f32x4 as = *(const LAS f32x4*)(acum + r * 128 + s0), ds = *(const LAS f32x4*)(dtt + r * 128 + s0);
; #pragma unroll
;                         for (int j = 0; j < 4; ++j) { const float v = X[sb][4 * qd + j] * __expf(al - as[j]) * ds[j]; mm[4 * qd + j] = (s0 + j < l) ? v : ((s0 + j == l) ? v + dsk : 0.f); }
.Lp5v0:
	v_lshl_add_u64 v[212:213], v[142:143], 0, s[94:95]
	v_lshl_add_u64 v[206:207], v[144:145], 0, s[94:95]
	v_mov_b32_e32 v164, 0
	v_add_co_u32_e32 v206, vcc, 0x1a900000, v206
	s_nop 1
	v_addc_co_u32_e32 v207, vcc, 0, v207, vcc
	v_bfe_u32 v164, v117, 5, 1
	v_lshlrev_b32_e32 v164, 3, v164
	v_add_co_u32_e32 v206, vcc, v164, v206
	s_nop 1
	v_addc_co_u32_e32 v207, vcc, 0, v207, vcc
	v_mov_b32_e32 v164, 0
	v_add_co_u32_e32 v184, vcc, 0x4000, v206
	s_nop 1
	v_addc_co_u32_e32 v185, vcc, 0, v207, vcc
	global_load_dword v159, v164, s[84:85]
	global_load_dwordx4 v[170:173], v[212:213], off
	global_load_dwordx4 v[174:177], v[212:213], off offset:32
	global_load_dwordx4 v[178:181], v[212:213], off offset:64
	global_load_dwordx4 v[220:223], v[212:213], off offset:96
	global_load_dwordx4 v[224:227], v[212:213], off offset:128
	global_load_dwordx4 v[228:231], v[212:213], off offset:160
	global_load_dwordx4 v[232:235], v[212:213], off offset:192
	global_load_dwordx4 v[208:211], v[212:213], off offset:224
	global_load_dwordx4 v[150:153], v[206:207], off offset:0
	global_load_dwordx4 v[154:157], v[206:207], off offset:32
	s_waitcnt vmcnt(0)
.Lp5v0_head:
	s_add_u32 s100, s94, 0x4000
	s_mov_b32 s101, 0
	ds_read_b32 v158, v141
	v_lshl_add_u64 v[212:213], v[142:143], 0, s[100:101]
	s_waitcnt vmcnt(10)
	v_mfma_f32_32x32x16_bf16 v[64:79], v[170:173], v[80:83], 0
	global_load_dwordx4 v[170:173], v[212:213], off
	s_waitcnt vmcnt(10)
	v_mfma_f32_32x32x16_bf16 v[64:79], v[174:177], v[84:87], v[64:79]
	global_load_dwordx4 v[174:177], v[212:213], off offset:32
	s_waitcnt vmcnt(10)
	v_mfma_f32_32x32x16_bf16 v[64:79], v[178:181], v[88:91], v[64:79]
	global_load_dwordx4 v[178:181], v[212:213], off offset:64
	s_waitcnt vmcnt(10)
	v_mfma_f32_32x32x16_bf16 v[64:79], v[220:223], v[92:95], v[64:79]
	global_load_dwordx4 v[220:223], v[212:213], off offset:96
	s_waitcnt vmcnt(10)
	v_mfma_f32_32x32x16_bf16 v[64:79], v[224:227], v[96:99], v[64:79]
	global_load_dwordx4 v[224:227], v[212:213], off offset:128
	s_waitcnt vmcnt(10)
	v_mfma_f32_32x32x16_bf16 v[64:79], v[228:231], v[100:103], v[64:79]
	global_load_dwordx4 v[228:231], v[212:213], off offset:160
	s_waitcnt vmcnt(10)
	v_mfma_f32_32x32x16_bf16 v[64:79], v[232:235], v[104:107], v[64:79]
	global_load_dwordx4 v[232:235], v[212:213], off offset:192
	s_waitcnt vmcnt(10)
	v_mfma_f32_32x32x16_bf16 v[64:79], v[208:211], v[108:111], v[64:79]
	global_load_dwordx4 v[208:211], v[212:213], off offset:224
	s_waitcnt lgkmcnt(0)
	v_mul_f32_e32 v164, 0x3fb8aa3b, v158
	v_exp_f32_e32 v165, v164
	v_mov_b32_e32 v158, v164
	s_nop 8
	v_mul_f32_e32 v64, v165, v64
	v_mul_f32_e32 v65, v165, v65
	v_mul_f32_e32 v66, v165, v66
	v_mul_f32_e32 v67, v165, v67
	v_mul_f32_e32 v68, v165, v68
	v_mul_f32_e32 v69, v165, v69
	v_mul_f32_e32 v70, v165, v70
	v_mul_f32_e32 v71, v165, v71
	v_mul_f32_e32 v72, v165, v72
	v_mul_f32_e32 v73, v165, v73
	v_mul_f32_e32 v74, v165, v74
	v_mul_f32_e32 v75, v165, v75
	v_mul_f32_e32 v76, v165, v76
	v_mul_f32_e32 v77, v165, v77
	v_mul_f32_e32 v78, v165, v78
	v_mul_f32_e32 v79, v165, v79
	ds_read_b128 v[236:239], v161 offset:4096
	ds_read_b128 v[250:253], v161 offset:4128
	s_waitcnt lgkmcnt(1)
	v_add_f32_e32 v164, v158, v236
	v_add_f32_e32 v165, v158, v237
	v_add_f32_e32 v244, v158, v238
	v_add_f32_e32 v245, v158, v239
	v_exp_f32_e32 v164, v164
	v_exp_f32_e32 v165, v165
	v_exp_f32_e32 v244, v244
	v_exp_f32_e32 v245, v245
	ds_read_b128 v[236:239], v161 offset:4160
	v_mul_f32_e32 v212, v0, v164
	v_mul_f32_e32 v213, v1, v165
	v_mul_f32_e32 v214, v2, v244
	v_mul_f32_e32 v215, v3, v245
	s_waitcnt lgkmcnt(1)
	v_add_f32_e32 v164, v158, v250
	v_add_f32_e32 v165, v158, v251
	v_add_f32_e32 v244, v158, v252
	v_add_f32_e32 v245, v158, v253
	v_exp_f32_e32 v164, v164
	v_exp_f32_e32 v165, v165
	v_exp_f32_e32 v244, v244
	v_exp_f32_e32 v245, v245
	ds_read_b128 v[250:253], v161 offset:4192
	v_mul_f32_e32 v216, v4, v164
	v_mul_f32_e32 v217, v5, v165
	v_mul_f32_e32 v218, v6, v244
	v_mul_f32_e32 v219, v7, v245
	s_waitcnt vmcnt(10)
	v_add_f32_e32 v169, v212, v159
	v_add_f32_e32 v183, v213, v159
	v_cmp_eq_u32_e32 vcc, 0, v160
	v_cmp_eq_u32_e64 s[100:101], 1, v160
	s_nop 0
	v_cndmask_b32_e32 v169, 0, v169, vcc
	v_cndmask_b32_e64 v183, 0, v183, s[100:101]
	v_cmp_lt_i32_e32 vcc, 0, v160
	v_cmp_lt_i32_e64 s[100:101], 1, v160
	s_nop 0
	v_cndmask_b32_e32 v212, v169, v212, vcc
	v_cndmask_b32_e64 v213, v183, v213, s[100:101]
	v_add_f32_e32 v169, v214, v159
	v_add_f32_e32 v183, v215, v159
	v_cmp_eq_u32_e32 vcc, 2, v160
	v_cmp_eq_u32_e64 s[100:101], 3, v160
	s_nop 0
	v_cndmask_b32_e32 v169, 0, v169, vcc
	v_cndmask_b32_e64 v183, 0, v183, s[100:101]
	v_cmp_lt_i32_e32 vcc, 2, v160
	v_cmp_lt_i32_e64 s[100:101], 3, v160
	s_nop 0
	v_cndmask_b32_e32 v214, v169, v214, vcc
	v_cndmask_b32_e64 v215, v183, v215, s[100:101]
	v_add_f32_e32 v169, v216, v159
	v_add_f32_e32 v183, v217, v159
	v_cmp_eq_u32_e32 vcc, 8, v160
	v_cmp_eq_u32_e64 s[100:101], 9, v160
	s_nop 0
	v_cndmask_b32_e32 v169, 0, v169, vcc
	v_cndmask_b32_e64 v183, 0, v183, s[100:101]
	v_cmp_lt_i32_e32 vcc, 8, v160
	v_cmp_lt_i32_e64 s[100:101], 9, v160
	s_nop 0
	v_cndmask_b32_e32 v216, v169, v216, vcc
	v_cndmask_b32_e64 v217, v183, v217, s[100:101]
	v_add_f32_e32 v169, v218, v159
	v_add_f32_e32 v183, v219, v159
	v_cmp_eq_u32_e32 vcc, 10, v160
	v_cmp_eq_u32_e64 s[100:101], 11, v160
	s_nop 0
	v_cndmask_b32_e32 v169, 0, v169, vcc
	v_cndmask_b32_e64 v183, 0, v183, s[100:101]
	v_cmp_lt_i32_e32 vcc, 10, v160
	v_cmp_lt_i32_e64 s[100:101], 11, v160
	s_nop 0
	v_cndmask_b32_e32 v218, v169, v218, vcc
	v_cndmask_b32_e64 v219, v183, v219, s[100:101]
	v_cvt_pk_bf16_f32 v212, v212, v213
	v_cvt_pk_bf16_f32 v213, v214, v215
	v_cvt_pk_bf16_f32 v214, v216, v217
	v_cvt_pk_bf16_f32 v215, v218, v219
	s_nop 0
	s_waitcnt vmcnt(8)
; #define LAS __attribute__((address_space(3)))
; __device__ __forceinline__ float bflo(unsigned u) { return __uint_as_float(u << 16); }
; __device__ __forceinline__ float bfhi(unsigned u) { return __uint_as_float(u & 0xffff0000u); }
; __device__ __forceinline__ f32x16 mfma32(bf16x8 a, bf16x8 b, f32x16 c) { return __builtin_amdgcn_mfma_f32_32x32x16_bf16(a, b, c, 0, 0, 0); }
; __device__ __forceinline__ void phase_ssd_y(const PT& p, LAS unsigned char* lds, int tid, int lane, int wave) {
;     ...
;                     for (int qd = 0; qd < 4; ++qd) {
;                         const int s0 = sb * 32 + 8 * qd + 4 * h;
;                         const f32x4 as = *(const LAS f32x4*)(acum + r * 128 + s0), ds = *(const LAS f32x4*)(dtt + r * 128 + s0);
; #pragma unroll
;                         for (int j = 0; j < 4; ++j) { const float v = X[sb][4 * qd + j] * __expf(al - as[j]) * ds[j]; mm[4 * qd + j] = (s0 + j < l) ? v : ((s0 + j == l) ? v + dsk : 0.f); }
;                     }
; #pragma unroll
;                     for (int s2 = 0; s2 < 2; ++s2) acc = mfma32(ld_frag8x2(xrow + sb * 32 + 16 * s2), pack_frag(mm, s2), acc);
;                 }
;             }
; #pragma unroll
;             for (int qd = 0; qd < 4; ++qd) {
;                 LAS u32x2* yp = (LAS u32x2*)(tile + l * SY_TP + (r * 64 + pb * 32 + 8 * qd + 4 * h) * 2); const u32x2 zz = *yp;
;                 const float y0 = acc[4 * qd] * bflo(zz.x), y1 = acc[4 * qd + 1] * bfhi(zz.x);
;                 const float y2 = acc[4 * qd + 2] * bflo(zz.y), y3 = acc[4 * qd + 3] * bfhi(zz.y);
;                 ssq += (y0 * y0 + y1 * y1) + (y2 * y2 + y3 * y3);
;                 u32x2 w; w.x = pk2(y0, y1); w.y = pk2(y2, y3); *yp = w;
;             }
	v_permlane32_swap_b32_e32 v150, v152
	v_permlane32_swap_b32_e32 v151, v153
	v_permlane32_swap_b32_e32 v154, v156
	v_permlane32_swap_b32_e32 v155, v157
	s_nop 1
	v_mfma_f32_32x32x16_bf16 v[64:79], v[150:153], v[212:215], v[64:79]
	s_waitcnt lgkmcnt(1)
	v_add_f32_e32 v164, v158, v236
	v_add_f32_e32 v165, v158, v237
	v_add_f32_e32 v244, v158, v238
	v_add_f32_e32 v245, v158, v239
	v_exp_f32_e32 v164, v164
	v_exp_f32_e32 v165, v165
	v_exp_f32_e32 v244, v244
	v_exp_f32_e32 v245, v245
	v_mul_f32_e32 v212, v8, v164
	v_mul_f32_e32 v213, v9, v165
	v_mul_f32_e32 v214, v10, v244
	v_mul_f32_e32 v215, v11, v245
	s_waitcnt lgkmcnt(0)
	v_add_f32_e32 v164, v158, v250
	v_add_f32_e32 v165, v158, v251
	v_add_f32_e32 v244, v158, v252
	v_add_f32_e32 v245, v158, v253
	v_exp_f32_e32 v164, v164
	v_exp_f32_e32 v165, v165
	v_exp_f32_e32 v244, v244
	v_exp_f32_e32 v245, v245
	v_mul_f32_e32 v216, v12, v164
	v_mul_f32_e32 v217, v13, v165
	v_mul_f32_e32 v218, v14, v244
	v_mul_f32_e32 v219, v15, v245
	v_add_f32_e32 v169, v212, v159
	v_add_f32_e32 v183, v213, v159
	v_cmp_eq_u32_e32 vcc, 16, v160
	v_cmp_eq_u32_e64 s[100:101], 17, v160
	s_nop 0
	v_cndmask_b32_e32 v169, 0, v169, vcc
	v_cndmask_b32_e64 v183, 0, v183, s[100:101]
	v_cmp_lt_i32_e32 vcc, 16, v160
	v_cmp_lt_i32_e64 s[100:101], 17, v160
	s_nop 0
	v_cndmask_b32_e32 v212, v169, v212, vcc
	v_cndmask_b32_e64 v213, v183, v213, s[100:101]
	v_add_f32_e32 v169, v214, v159
	v_add_f32_e32 v183, v215, v159
	v_cmp_eq_u32_e32 vcc, 18, v160
	v_cmp_eq_u32_e64 s[100:101], 19, v160
	s_nop 0
	v_cndmask_b32_e32 v169, 0, v169, vcc
	v_cndmask_b32_e64 v183, 0, v183, s[100:101]
	v_cmp_lt_i32_e32 vcc, 18, v160
	v_cmp_lt_i32_e64 s[100:101], 19, v160
	s_nop 0
	v_cndmask_b32_e32 v214, v169, v214, vcc
	v_cndmask_b32_e64 v215, v183, v215, s[100:101]
	v_add_f32_e32 v169, v216, v159
	v_add_f32_e32 v183, v217, v159
	v_cmp_eq_u32_e32 vcc, 24, v160
	v_cmp_eq_u32_e64 s[100:101], 25, v160
	s_nop 0
	v_cndmask_b32_e32 v169, 0, v169, vcc
	v_cndmask_b32_e64 v183, 0, v183, s[100:101]
	v_cmp_lt_i32_e32 vcc, 24, v160
	v_cmp_lt_i32_e64 s[100:101], 25, v160
	s_nop 0
	v_cndmask_b32_e32 v216, v169, v216, vcc
	v_cndmask_b32_e64 v217, v183, v217, s[100:101]
	v_add_f32_e32 v169, v218, v159
	v_add_f32_e32 v183, v219, v159
	v_cmp_eq_u32_e32 vcc, 26, v160
	v_cmp_eq_u32_e64 s[100:101], 27, v160
	s_nop 0
	v_cndmask_b32_e32 v169, 0, v169, vcc
	v_cndmask_b32_e64 v183, 0, v183, s[100:101]
	v_cmp_lt_i32_e32 vcc, 26, v160
	v_cmp_lt_i32_e64 s[100:101], 27, v160
	s_nop 0
	v_cndmask_b32_e32 v218, v169, v218, vcc
	v_cndmask_b32_e64 v219, v183, v219, s[100:101]
	s_cmp_eq_u32 s94, 0x1c000
	s_cselect_b32 s100, 0, 4
	s_add_u32 s84, s84, s100
	s_addc_u32 s85, s85, 0
	v_mov_b32_e32 v164, 0
	global_load_dword v159, v164, s[84:85]
	v_cvt_pk_bf16_f32 v212, v212, v213
	v_cvt_pk_bf16_f32 v213, v214, v215
	v_cvt_pk_bf16_f32 v214, v216, v217
	v_cvt_pk_bf16_f32 v215, v218, v219
	s_nop 0
	s_nop 0
	v_mfma_f32_32x32x16_bf16 v[64:79], v[154:157], v[212:215], v[64:79]
	global_load_dwordx4 v[150:153], v[184:185], off offset:0
	global_load_dwordx4 v[154:157], v[184:185], off offset:32
	s_nop 10
	ds_read_b64 v[216:217], v162 offset:0
	s_waitcnt lgkmcnt(0)
	v_lshlrev_b32_e32 v169, 16, v216
	v_and_b32_e32 v183, 0xffff0000, v216
	v_lshlrev_b32_e32 v254, 16, v217
	v_and_b32_e32 v255, 0xffff0000, v217
	v_mul_f32_e32 v169, v64, v169
	v_mul_f32_e32 v183, v65, v183
	v_mul_f32_e32 v254, v66, v254
	v_mul_f32_e32 v255, v67, v255
	v_mul_f32_e32 v164, v169, v169
	v_mul_f32_e32 v165, v254, v254
	v_fmac_f32_e32 v164, v183, v183
	v_fmac_f32_e32 v165, v255, v255
	v_cvt_pk_bf16_f32 v216, v169, v183
	v_cvt_pk_bf16_f32 v217, v254, v255
	v_add_f32_e32 v164, v164, v165
	ds_write_b64 v162, v[216:217] offset:0
	v_add_f32_e32 v126, v126, v164
	ds_read_b64 v[216:217], v162 offset:16
	s_waitcnt lgkmcnt(0)
	v_lshlrev_b32_e32 v169, 16, v216
	v_and_b32_e32 v183, 0xffff0000, v216
	v_lshlrev_b32_e32 v254, 16, v217
	v_and_b32_e32 v255, 0xffff0000, v217
	v_mul_f32_e32 v169, v68, v169
	v_mul_f32_e32 v183, v69, v183
	v_mul_f32_e32 v254, v70, v254
	v_mul_f32_e32 v255, v71, v255
	v_mul_f32_e32 v164, v169, v169
	v_mul_f32_e32 v165, v254, v254
	v_fmac_f32_e32 v164, v183, v183
	v_fmac_f32_e32 v165, v255, v255
	v_cvt_pk_bf16_f32 v216, v169, v183
	v_cvt_pk_bf16_f32 v217, v254, v255
	v_add_f32_e32 v164, v164, v165
	ds_write_b64 v162, v[216:217] offset:16
	v_add_f32_e32 v126, v126, v164
	ds_read_b64 v[216:217], v162 offset:32
	s_waitcnt lgkmcnt(0)
	v_lshlrev_b32_e32 v169, 16, v216
	v_and_b32_e32 v183, 0xffff0000, v216
	v_lshlrev_b32_e32 v254, 16, v217
	v_and_b32_e32 v255, 0xffff0000, v217
	v_mul_f32_e32 v169, v72, v169
	v_mul_f32_e32 v183, v73, v183
	v_mul_f32_e32 v254, v74, v254
	v_mul_f32_e32 v255, v75, v255
	v_mul_f32_e32 v164, v169, v169
	v_mul_f32_e32 v165, v254, v254
	v_fmac_f32_e32 v164, v183, v183
	v_fmac_f32_e32 v165, v255, v255
	v_cvt_pk_bf16_f32 v216, v169, v183
	v_cvt_pk_bf16_f32 v217, v254, v255
	v_add_f32_e32 v164, v164, v165
	ds_write_b64 v162, v[216:217] offset:32
	v_add_f32_e32 v126, v126, v164
	ds_read_b64 v[216:217], v162 offset:48
	s_waitcnt lgkmcnt(0)
	v_lshlrev_b32_e32 v169, 16, v216
	v_and_b32_e32 v183, 0xffff0000, v216
	v_lshlrev_b32_e32 v254, 16, v217
	v_and_b32_e32 v255, 0xffff0000, v217
	v_mul_f32_e32 v169, v76, v169
	v_mul_f32_e32 v183, v77, v183
	v_mul_f32_e32 v254, v78, v254
	v_mul_f32_e32 v255, v79, v255
	v_mul_f32_e32 v164, v169, v169
	v_mul_f32_e32 v165, v254, v254
	v_fmac_f32_e32 v164, v183, v183
	v_fmac_f32_e32 v165, v255, v255
	v_cvt_pk_bf16_f32 v216, v169, v183
	v_cvt_pk_bf16_f32 v217, v254, v255
	v_add_f32_e32 v164, v164, v165
	ds_write_b64 v162, v[216:217] offset:48
	v_add_f32_e32 v126, v126, v164
	v_add_u32_e32 v161, 0x200, v161
	v_add_u32_e32 v141, 0x200, v141
	v_add_u32_e32 v162, 0x80, v162
	v_mov_b32_e32 v206, v184
	v_mov_b32_e32 v207, v185
	v_add_co_u32_e32 v184, vcc, 0x4000, v184
	s_nop 1
	v_addc_co_u32_e32 v185, vcc, 0, v185, vcc
	s_add_u32 s94, s94, 0x4000
	s_cmp_eq_u32 s94, 0x20000
	s_cbranch_scc0 .Lp5v0_head
	s_branch .Lp5v_exit
